# grid-size-generic conversion routine (strides from gridDim) plus nt hint on the one-shot f32 weight loads
# speedup vs baseline: 1.0117x; 1.0014x over previous
; __device__ __forceinline__ int opaque_tid() { int t = threadIdx.x; asm volatile("" : "+v"(t)); return t; }
; #define CVT_LOAD(tile_) do { const int k0_ = ((tile_) / ntn) << 7, n0_ = ((tile_) % ntn) << 6; \
;         _Pragma("unroll") for (int pp = 0; pp < 4; ++pp) pv[pp] = *(const float4*)(src + (size_t)(k0_ + lk + 32 * pp) * N + n0_ + ln4); } while (0)
; __device__ __forceinline__ void convT_job(const float* __restrict__ src, bf16_t* __restrict__ dst, int K, int N, int mode, float* t) {
;     const int tid = opaque_tid(), ntn = N >> 6, ntiles = (K >> 7) * ntn;
;     const int lk = tid >> 4, ln4 = (tid & 15) * 4;
;     float4 pv[4];
;     ...
;     int tile = blockIdx.x;
;     if (tile < ntiles) CVT_LOAD(tile);
; #pragma unroll 1
;     for (; tile < ntiles; tile += gridDim.x) {
;         const int k0 = (tile / ntn) << 7, n0 = (tile % ntn) << 6;
; #pragma unroll
;         for (int pp = 0; pp < 4; ++pp) { const int k = lk + 32 * pp; t[k * 65 + ln4] = pv[pp].x; t[k * 65 + ln4 + 1] = pv[pp].y; t[k * 65 + ln4 + 2] = pv[pp].z; t[k * 65 + ln4 + 3] = pv[pp].w; }
;         if (tile + (int)gridDim.x < ntiles) CVT_LOAD(tile + (int)gridDim.x);
; __device__ __forceinline__ void run_phase(const Params& p, int ph, unsigned char* smem, int rep) {
;     ...
;     } else if (k == 3) {
;         gemm_in(XB, (const bf16_t*)(p.ws + OFF_IN + (size_t)l * SZ_IN), H);
.LBB0_543:
	v_readlane_b32 s57, v255, 23
	s_mov_b32 s56, 0x1c488000
	s_barrier
	s_load_dword s98, s[96:97], 0x0
	s_movk_i32 s99, 0x580
	s_waitcnt lgkmcnt(0)
.Ldf_mod:
	s_cmp_ge_u32 s99, s98
	s_cbranch_scc0 .Ldf_moddone
	s_sub_u32 s99, s99, s98
	s_branch .Ldf_mod
.Ldf_moddone:
	s_cmp_lt_u32 s60, s99
	s_cbranch_scc1 .Ldf_end
	s_sub_u32 s98, s98, s99
	v_readlane_b32 s53, v255, 33
	v_lshrrev_b32_e32 v6, 6, v234
	v_and_b32_e32 v25, 63, v234
	v_lshrrev_b32_e32 v26, 3, v234
	v_readfirstlane_b32 s46, v6
	v_and_b32_e32 v27, 7, v234
	v_readlane_b32 s54, v255, 28
	v_readlane_b32 s55, v255, 29
	s_lshl_b32 s46, s46, 12
	v_lshrrev_b32_e32 v28, 2, v26
	v_xor_b32_e32 v28, v28, v27
	v_lshlrev_b32_e32 v28, 4, v28
	v_and_b32_e32 v29, 3, v26
	v_lshl_or_b32 v28, v29, 2, v28
	v_lshl_or_b32 v4, v27, 12, v28
	v_lshrrev_b32_e32 v30, 4, v25
	v_lshl_add_u32 v30, v6, 4, v30
	v_and_b32_e32 v31, 15, v25
	v_xor_b32_e32 v31, v31, v6
	v_lshlrev_b32_e32 v31, 4, v31
	v_lshlrev_b32_e32 v27, 5, v27
	s_sub_u32 s40, s60, s99
	s_cmp_lt_u32 s40, 1408
	s_cbranch_scc0 .Ldf_dgate_skip
	s_mul_i32 s0, s53, 2
	s_add_u32 s0, s0, 1
	s_mul_hi_u32 s1, s0, 0x2c00000
	s_mul_i32 s2, s0, 0x2c00000
	s_add_u32 s50, s70, s2
	s_addc_u32 s51, s71, s1
	s_mul_i32 s52, s0, 0x2c00000
	s_add_u32 s52, s52, 0x8000
	v_mov_b32_e32 v29, 0x5800
	v_mov_b32_e32 v28, 0x1000
	v_mad_u32_u24 v0, v30, v29, v31
	v_mad_u32_u24 v5, v26, v28, v27
	v_add_u32_e32 v1, 0x16000, v0
	v_add_u32_e32 v2, 0x2c000, v0
	v_add_u32_e32 v3, 0x42000, v0
	s_barrier
	s_mov_b32 s41, 0
	s_mov_b32 s47, s40
	s_mov_b32 s48, s46
	s_mul_hi_u32 s0, s47, 0x2e8ba3
	s_mul_i32 s1, s0, 1408
	s_sub_u32 s1, s47, s1
	s_mul_hi_u32 s2, s1, 0x2e8ba2f
	s_mul_i32 s8, s2, 88
	s_sub_u32 s8, s1, s8
	s_mul_i32 s9, s0, 0x2c00000
	s_mul_i32 s28, s2, 0x2c0000
	s_add_u32 s9, s9, s28
	s_lshl_b32 s8, s8, 8
	s_add_u32 s9, s9, s8
	s_add_u32 s42, s50, s9
	s_addc_u32 s43, s51, 0
	s_mov_b32 m0, s48
	s_add_u32 s49, s48, 0x400
	global_load_lds_dwordx4 v0, s[42:43] nt
	s_mov_b32 m0, s49
	s_add_u32 s49, s48, 0x800
	global_load_lds_dwordx4 v1, s[42:43] nt
	s_mov_b32 m0, s49
	s_add_u32 s49, s48, 0xc00
	global_load_lds_dwordx4 v2, s[42:43] nt
	s_mov_b32 m0, s49
	s_nop 0
	global_load_lds_dwordx4 v3, s[42:43] nt
	global_load_dword v24, v173, s[70:71]
	global_load_dword v24, v173, s[70:71]
	s_add_u32 s47, s40, s98
	s_add_u32 s48, s46, 0x8000
	s_cmp_lt_u32 s47, 1408
	s_cbranch_scc0 .Ldf_dgate_pd1
	s_mul_hi_u32 s0, s47, 0x2e8ba3
	s_mul_i32 s1, s0, 1408
	s_sub_u32 s1, s47, s1
	s_mul_hi_u32 s2, s1, 0x2e8ba2f
	s_mul_i32 s8, s2, 88
	s_sub_u32 s8, s1, s8
	s_mul_i32 s9, s0, 0x2c00000
	s_mul_i32 s28, s2, 0x2c0000
	s_add_u32 s9, s9, s28
	s_lshl_b32 s8, s8, 8
	s_add_u32 s9, s9, s8
	s_add_u32 s42, s50, s9
	s_addc_u32 s43, s51, 0
	s_mov_b32 m0, s48
	s_add_u32 s49, s48, 0x400
	global_load_lds_dwordx4 v0, s[42:43] nt
	s_mov_b32 m0, s49
	s_add_u32 s49, s48, 0x800
	global_load_lds_dwordx4 v1, s[42:43] nt
	s_mov_b32 m0, s49
	s_add_u32 s49, s48, 0xc00
	global_load_lds_dwordx4 v2, s[42:43] nt
	s_mov_b32 m0, s49
	s_nop 0
	global_load_lds_dwordx4 v3, s[42:43] nt
	s_branch .Ldf_dgate_pj1

; #define CVT_LOAD(tile_) do { const int k0_ = ((tile_) / ntn) << 7, n0_ = ((tile_) % ntn) << 6; \
;         _Pragma("unroll") for (int pp = 0; pp < 4; ++pp) pv[pp] = *(const float4*)(src + (size_t)(k0_ + lk + 32 * pp) * N + n0_ + ln4); } while (0)
; __device__ __forceinline__ void convT_job(const float* __restrict__ src, bf16_t* __restrict__ dst, int K, int N, int mode, float* t) {
;     ...
;         if (tile + (int)gridDim.x < ntiles) CVT_LOAD(tile + (int)gridDim.x);
.Ldf_dgate_pj1:
	global_load_dword v24, v173, s[70:71]
	global_load_dword v24, v173, s[70:71]
	s_lshl_b32 s47, s98, 1
	s_add_u32 s47, s47, s40
	s_add_u32 s48, s46, 0x10000
	s_cmp_lt_u32 s47, 1408
	s_cbranch_scc0 .Ldf_dgate_pd2
	s_mul_hi_u32 s0, s47, 0x2e8ba3
	s_mul_i32 s1, s0, 1408
	s_sub_u32 s1, s47, s1
	s_mul_hi_u32 s2, s1, 0x2e8ba2f
	s_mul_i32 s8, s2, 88
	s_sub_u32 s8, s1, s8
	s_mul_i32 s9, s0, 0x2c00000
	s_mul_i32 s28, s2, 0x2c0000
	s_add_u32 s9, s9, s28
	s_lshl_b32 s8, s8, 8
	s_add_u32 s9, s9, s8
	s_add_u32 s42, s50, s9
	s_addc_u32 s43, s51, 0
	s_mov_b32 m0, s48
	s_add_u32 s49, s48, 0x400
	global_load_lds_dwordx4 v0, s[42:43] nt
	s_mov_b32 m0, s49
	s_add_u32 s49, s48, 0x800
	global_load_lds_dwordx4 v1, s[42:43] nt
	s_mov_b32 m0, s49
	s_add_u32 s49, s48, 0xc00
	global_load_lds_dwordx4 v2, s[42:43] nt
	s_mov_b32 m0, s49
	s_nop 0
	global_load_lds_dwordx4 v3, s[42:43] nt
	s_branch .Ldf_dgate_pj2

; #define CVT_LOAD(tile_) do { const int k0_ = ((tile_) / ntn) << 7, n0_ = ((tile_) % ntn) << 6; \
;         _Pragma("unroll") for (int pp = 0; pp < 4; ++pp) pv[pp] = *(const float4*)(src + (size_t)(k0_ + lk + 32 * pp) * N + n0_ + ln4); } while (0)
; __device__ __forceinline__ void convT_job(const float* __restrict__ src, bf16_t* __restrict__ dst, int K, int N, int mode, float* t) {
;     ...
; #pragma unroll 1
;     for (; tile < ntiles; tile += gridDim.x) {
;         const int k0 = (tile / ntn) << 7, n0 = (tile % ntn) << 6;
; #pragma unroll
;         for (int pp = 0; pp < 4; ++pp) { const int k = lk + 32 * pp; t[k * 65 + ln4] = pv[pp].x; t[k * 65 + ln4 + 1] = pv[pp].y; t[k * 65 + ln4 + 2] = pv[pp].z; t[k * 65 + ln4 + 3] = pv[pp].w; }
;         if (tile + (int)gridDim.x < ntiles) CVT_LOAD(tile + (int)gridDim.x);
.Ldf_dgate_loop:
	s_waitcnt vmcnt(14)
	s_barrier
	s_mul_i32 s47, s98, 3
	s_add_u32 s47, s47, s40
	s_add_u32 s48, s41, 0x18000
	s_and_b32 s48, s48, 0x1ffff
	s_add_u32 s48, s48, s46
	s_cmp_lt_u32 s47, 1408
	s_cbranch_scc0 .Ldf_dgate_ld
	s_mul_hi_u32 s0, s47, 0x2e8ba3
	s_mul_i32 s1, s0, 1408
	s_sub_u32 s1, s47, s1
	s_mul_hi_u32 s2, s1, 0x2e8ba2f
	s_mul_i32 s8, s2, 88
	s_sub_u32 s8, s1, s8
	s_mul_i32 s9, s0, 0x2c00000
	s_mul_i32 s28, s2, 0x2c0000
	s_add_u32 s9, s9, s28
	s_lshl_b32 s8, s8, 8
	s_add_u32 s9, s9, s8
	s_add_u32 s42, s50, s9
	s_addc_u32 s43, s51, 0
	s_mov_b32 m0, s48
	s_add_u32 s49, s48, 0x400
	global_load_lds_dwordx4 v0, s[42:43] nt
	s_mov_b32 m0, s49
	s_add_u32 s49, s48, 0x800
	global_load_lds_dwordx4 v1, s[42:43] nt
	s_mov_b32 m0, s49
	s_add_u32 s49, s48, 0xc00
	global_load_lds_dwordx4 v2, s[42:43] nt
	s_mov_b32 m0, s49
	s_nop 0
	global_load_lds_dwordx4 v3, s[42:43] nt
	s_branch .Ldf_dgate_lj

; __device__ __forceinline__ unsigned cvt_pk_bf16(float lo, float hi) { unsigned r; asm volatile("v_cvt_pk_bf16_f32 %0, %1, %2" : "=v"(r) : "v"(lo), "v"(hi)); return r; }
; __device__ __forceinline__ void lds_barrier() { asm volatile("s_waitcnt lgkmcnt(0)" ::: "memory"); __builtin_amdgcn_s_barrier(); asm volatile("" ::: "memory"); }
; __device__ __forceinline__ void convT_job(const float* __restrict__ src, bf16_t* __restrict__ dst, int K, int N, int mode, float* t) {
;     ...
;         lds_barrier();
;         const int n = tid >> 3, k16 = (tid & 7) * 16;
;         float v[16];
; #pragma unroll
;         for (int j = 0; j < 16; ++j) v[j] = t[(k16 + j) * 65 + n];
;         const int nn = n0 + n;
;         const int row = mode == 0 ? nn : (256 * (nn >> 7) + (nn & 127) + (mode == 2 ? 128 : 0));
;         u32x4 w0, w1; w0.x = cvt_pk_bf16(v[0], v[1]); w0.y = cvt_pk_bf16(v[2], v[3]); w0.z = cvt_pk_bf16(v[4], v[5]); w0.w = cvt_pk_bf16(v[6], v[7]);
;         w1.x = cvt_pk_bf16(v[8], v[9]); w1.y = cvt_pk_bf16(v[10], v[11]); w1.z = cvt_pk_bf16(v[12], v[13]); w1.w = cvt_pk_bf16(v[14], v[15]);
;         bf16_t* d = dst + (size_t)row * K + k0 + k16;
;         *(u32x4*)d = w0; *(u32x4*)(d + 8) = w1;
;         lds_barrier();
; __device__ __forceinline__ void phase_convert(const Params& p, unsigned char* smem) {
;     ...
;             convT_job(p.in[3] + wo, gu, 2048, 5632, 1, t);
;             convT_job(p.in[4] + wo, gu, 2048, 5632, 2, t);
.Ldf_dgate_lj:
	v_add_u32_e32 v7, s41, v4
	ds_read2st64_b32 v[8:9], v7 offset0:0 offset1:1
	ds_read2st64_b32 v[10:11], v7 offset0:2 offset1:3
	ds_read2st64_b32 v[12:13], v7 offset0:4 offset1:5
	ds_read2st64_b32 v[14:15], v7 offset0:6 offset1:7
	ds_read2st64_b32 v[16:17], v7 offset0:8 offset1:9
	ds_read2st64_b32 v[18:19], v7 offset0:10 offset1:11
	ds_read2st64_b32 v[20:21], v7 offset0:12 offset1:13
	ds_read2st64_b32 v[22:23], v7 offset0:14 offset1:15
	s_mul_hi_u32 s0, s40, 0x2e8ba3
	s_mul_i32 s1, s0, 1408
	s_sub_u32 s1, s40, s1
	s_mul_hi_u32 s2, s1, 0x2e8ba2f
	s_mul_i32 s8, s2, 88
	s_sub_u32 s8, s1, s8
	s_lshr_b32 s9, s8, 1
	s_lshl_b32 s9, s9, 8
	s_and_b32 s28, s8, 1
	s_lshl_b32 s28, s28, 6
	s_add_u32 s9, s9, s28
	s_mul_i32 s9, s9, 0x1000
	s_mul_i32 s28, s0, 0x2c00000
	s_add_u32 s9, s9, s28
	s_lshl_b32 s2, s2, 8
	s_add_u32 s9, s9, s2
	s_add_u32 s9, s9, s52
	s_add_u32 s44, s54, s9
	s_addc_u32 s45, s55, 0
	s_waitcnt lgkmcnt(6)
	v_cvt_pk_bf16_f32 v8, v8, v9
	v_cvt_pk_bf16_f32 v9, v10, v11
	s_waitcnt lgkmcnt(4)
	v_cvt_pk_bf16_f32 v10, v12, v13
	v_cvt_pk_bf16_f32 v11, v14, v15
	s_waitcnt lgkmcnt(2)
	v_cvt_pk_bf16_f32 v12, v16, v17
	v_cvt_pk_bf16_f32 v13, v18, v19
	s_waitcnt lgkmcnt(0)
	v_cvt_pk_bf16_f32 v14, v20, v21
	v_cvt_pk_bf16_f32 v15, v22, v23
	global_store_dwordx4 v5, v[8:11], s[44:45]
	global_store_dwordx4 v5, v[12:15], s[44:45] offset:16
	s_add_u32 s40, s40, s98
	s_add_u32 s41, s41, 0x8000
	s_and_b32 s41, s41, 0x1ffff
	s_cmp_lt_u32 s40, 1408
	s_cbranch_scc1 .Ldf_dgate_loop
.Ldf_dgate_skip:
	s_sub_u32 s40, s60, s99
	s_cmp_lt_u32 s40, 1408
	s_cbranch_scc0 .Ldf_dup_skip
	s_mul_i32 s0, s53, 2
	s_add_u32 s0, s0, 1
	s_mul_hi_u32 s1, s0, 0x2c00000
	s_mul_i32 s2, s0, 0x2c00000
	s_add_u32 s50, s72, s2
	s_addc_u32 s51, s73, s1
	s_mul_i32 s52, s0, 0x2c00000
	s_add_u32 s52, s52, 0x8000
	v_mov_b32_e32 v29, 0x5800
	v_mov_b32_e32 v28, 0x1000
	v_mad_u32_u24 v0, v30, v29, v31
	v_mad_u32_u24 v5, v26, v28, v27
	v_add_u32_e32 v1, 0x16000, v0
	v_add_u32_e32 v2, 0x2c000, v0
	v_add_u32_e32 v3, 0x42000, v0
	s_barrier
	s_mov_b32 s41, 0
	s_mov_b32 s47, s40
	s_mov_b32 s48, s46
	s_mul_hi_u32 s0, s47, 0x2e8ba3
	s_mul_i32 s1, s0, 1408
	s_sub_u32 s1, s47, s1
	s_mul_hi_u32 s2, s1, 0x2e8ba2f
	s_mul_i32 s8, s2, 88
	s_sub_u32 s8, s1, s8
	s_mul_i32 s9, s0, 0x2c00000
	s_mul_i32 s28, s2, 0x2c0000
	s_add_u32 s9, s9, s28
	s_lshl_b32 s8, s8, 8
	s_add_u32 s9, s9, s8
	s_add_u32 s42, s50, s9
	s_addc_u32 s43, s51, 0
	s_mov_b32 m0, s48
	s_add_u32 s49, s48, 0x400
	global_load_lds_dwordx4 v0, s[42:43] nt
	s_mov_b32 m0, s49
	s_add_u32 s49, s48, 0x800
	global_load_lds_dwordx4 v1, s[42:43] nt
	s_mov_b32 m0, s49
	s_add_u32 s49, s48, 0xc00
	global_load_lds_dwordx4 v2, s[42:43] nt
	s_mov_b32 m0, s49
	s_nop 0
	global_load_lds_dwordx4 v3, s[42:43] nt
	global_load_dword v24, v173, s[72:73]
	global_load_dword v24, v173, s[72:73]
	s_add_u32 s47, s40, s98
	s_add_u32 s48, s46, 0x8000
	s_cmp_lt_u32 s47, 1408
	s_cbranch_scc0 .Ldf_dup_pd1
	s_mul_hi_u32 s0, s47, 0x2e8ba3
	s_mul_i32 s1, s0, 1408
	s_sub_u32 s1, s47, s1
	s_mul_hi_u32 s2, s1, 0x2e8ba2f
	s_mul_i32 s8, s2, 88
	s_sub_u32 s8, s1, s8
	s_mul_i32 s9, s0, 0x2c00000
	s_mul_i32 s28, s2, 0x2c0000
	s_add_u32 s9, s9, s28
	s_lshl_b32 s8, s8, 8
	s_add_u32 s9, s9, s8
	s_add_u32 s42, s50, s9
	s_addc_u32 s43, s51, 0
	s_mov_b32 m0, s48
	s_add_u32 s49, s48, 0x400
	global_load_lds_dwordx4 v0, s[42:43] nt
	s_mov_b32 m0, s49
	s_add_u32 s49, s48, 0x800
	global_load_lds_dwordx4 v1, s[42:43] nt
	s_mov_b32 m0, s49
	s_add_u32 s49, s48, 0xc00
	global_load_lds_dwordx4 v2, s[42:43] nt
	s_mov_b32 m0, s49
	s_nop 0
	global_load_lds_dwordx4 v3, s[42:43] nt
	s_branch .Ldf_dup_pj1

; #define CVT_LOAD(tile_) do { const int k0_ = ((tile_) / ntn) << 7, n0_ = ((tile_) % ntn) << 6; \
;         _Pragma("unroll") for (int pp = 0; pp < 4; ++pp) pv[pp] = *(const float4*)(src + (size_t)(k0_ + lk + 32 * pp) * N + n0_ + ln4); } while (0)
; __device__ __forceinline__ void convT_job(const float* __restrict__ src, bf16_t* __restrict__ dst, int K, int N, int mode, float* t) {
;     ...
;         if (tile + (int)gridDim.x < ntiles) CVT_LOAD(tile + (int)gridDim.x);
.Ldf_dup_pj1:
	global_load_dword v24, v173, s[72:73]
	global_load_dword v24, v173, s[72:73]
	s_lshl_b32 s47, s98, 1
	s_add_u32 s47, s47, s40
	s_add_u32 s48, s46, 0x10000
	s_cmp_lt_u32 s47, 1408
	s_cbranch_scc0 .Ldf_dup_pd2
	s_mul_hi_u32 s0, s47, 0x2e8ba3
	s_mul_i32 s1, s0, 1408
	s_sub_u32 s1, s47, s1
	s_mul_hi_u32 s2, s1, 0x2e8ba2f
	s_mul_i32 s8, s2, 88
	s_sub_u32 s8, s1, s8
	s_mul_i32 s9, s0, 0x2c00000
	s_mul_i32 s28, s2, 0x2c0000
	s_add_u32 s9, s9, s28
	s_lshl_b32 s8, s8, 8
	s_add_u32 s9, s9, s8
	s_add_u32 s42, s50, s9
	s_addc_u32 s43, s51, 0
	s_mov_b32 m0, s48
	s_add_u32 s49, s48, 0x400
	global_load_lds_dwordx4 v0, s[42:43] nt
	s_mov_b32 m0, s49
	s_add_u32 s49, s48, 0x800
	global_load_lds_dwordx4 v1, s[42:43] nt
	s_mov_b32 m0, s49
	s_add_u32 s49, s48, 0xc00
	global_load_lds_dwordx4 v2, s[42:43] nt
	s_mov_b32 m0, s49
	s_nop 0
	global_load_lds_dwordx4 v3, s[42:43] nt
	s_branch .Ldf_dup_pj2

; __device__ __forceinline__ unsigned cvt_pk_bf16(float lo, float hi) { unsigned r; asm volatile("v_cvt_pk_bf16_f32 %0, %1, %2" : "=v"(r) : "v"(lo), "v"(hi)); return r; }
; __device__ __forceinline__ void lds_barrier() { asm volatile("s_waitcnt lgkmcnt(0)" ::: "memory"); __builtin_amdgcn_s_barrier(); asm volatile("" ::: "memory"); }
; __device__ __forceinline__ void convT_job(const float* __restrict__ src, bf16_t* __restrict__ dst, int K, int N, int mode, float* t) {
;     ...
;         lds_barrier();
;         const int n = tid >> 3, k16 = (tid & 7) * 16;
;         float v[16];
; #pragma unroll
;         for (int j = 0; j < 16; ++j) v[j] = t[(k16 + j) * 65 + n];
;         const int nn = n0 + n;
;         const int row = mode == 0 ? nn : (256 * (nn >> 7) + (nn & 127) + (mode == 2 ? 128 : 0));
;         u32x4 w0, w1; w0.x = cvt_pk_bf16(v[0], v[1]); w0.y = cvt_pk_bf16(v[2], v[3]); w0.z = cvt_pk_bf16(v[4], v[5]); w0.w = cvt_pk_bf16(v[6], v[7]);
;         w1.x = cvt_pk_bf16(v[8], v[9]); w1.y = cvt_pk_bf16(v[10], v[11]); w1.z = cvt_pk_bf16(v[12], v[13]); w1.w = cvt_pk_bf16(v[14], v[15]);
;         bf16_t* d = dst + (size_t)row * K + k0 + k16;
;         *(u32x4*)d = w0; *(u32x4*)(d + 8) = w1;
;         lds_barrier();
; __device__ __forceinline__ void phase_convert(const Params& p, unsigned char* smem) {
;     ...
;             convT_job(p.in[5] + wo, (bf16_t*)(p.ws + OFF_DN + (size_t)(l * 2 + f) * SZ_DN), 5632, 2048, 0, t);
.Ldf_dup_lj:
	v_add_u32_e32 v7, s41, v4
	ds_read2st64_b32 v[8:9], v7 offset0:0 offset1:1
	ds_read2st64_b32 v[10:11], v7 offset0:2 offset1:3
	ds_read2st64_b32 v[12:13], v7 offset0:4 offset1:5
	ds_read2st64_b32 v[14:15], v7 offset0:6 offset1:7
	ds_read2st64_b32 v[16:17], v7 offset0:8 offset1:9
	ds_read2st64_b32 v[18:19], v7 offset0:10 offset1:11
	ds_read2st64_b32 v[20:21], v7 offset0:12 offset1:13
	ds_read2st64_b32 v[22:23], v7 offset0:14 offset1:15
	s_mul_hi_u32 s0, s40, 0x2e8ba3
	s_mul_i32 s1, s0, 1408
	s_sub_u32 s1, s40, s1
	s_mul_hi_u32 s2, s1, 0x2e8ba2f
	s_mul_i32 s8, s2, 88
	s_sub_u32 s8, s1, s8
	s_lshr_b32 s9, s8, 1
	s_lshl_b32 s9, s9, 8
	s_and_b32 s28, s8, 1
	s_lshl_b32 s28, s28, 6
	s_add_u32 s9, s9, s28
	s_add_u32 s9, s9, 128
	s_mul_i32 s9, s9, 0x1000
	s_mul_i32 s28, s0, 0x2c00000
	s_add_u32 s9, s9, s28
	s_lshl_b32 s2, s2, 8
	s_add_u32 s9, s9, s2
	s_add_u32 s9, s9, s52
	s_add_u32 s44, s54, s9
	s_addc_u32 s45, s55, 0
	s_waitcnt lgkmcnt(6)
	v_cvt_pk_bf16_f32 v8, v8, v9
	v_cvt_pk_bf16_f32 v9, v10, v11
	s_waitcnt lgkmcnt(4)
	v_cvt_pk_bf16_f32 v10, v12, v13
	v_cvt_pk_bf16_f32 v11, v14, v15
	s_waitcnt lgkmcnt(2)
	v_cvt_pk_bf16_f32 v12, v16, v17
	v_cvt_pk_bf16_f32 v13, v18, v19
	s_waitcnt lgkmcnt(0)
	v_cvt_pk_bf16_f32 v14, v20, v21
	v_cvt_pk_bf16_f32 v15, v22, v23
	global_store_dwordx4 v5, v[8:11], s[44:45]
	global_store_dwordx4 v5, v[12:15], s[44:45] offset:16
	s_add_u32 s40, s40, s98
	s_add_u32 s41, s41, 0x8000
	s_and_b32 s41, s41, 0x1ffff
	s_cmp_lt_u32 s40, 1408
	s_cbranch_scc1 .Ldf_dup_loop
.Ldf_dup_skip:
	s_sub_u32 s40, s60, s99
	s_cmp_lt_u32 s40, 1408
	s_cbranch_scc0 .Ldf_ddown_skip
	s_mul_i32 s0, s53, 2
	s_add_u32 s0, s0, 1
	s_mul_hi_u32 s1, s0, 0x2c00000
	s_mul_i32 s2, s0, 0x2c00000
	s_add_u32 s50, s74, s2
	s_addc_u32 s51, s75, s1
	s_mul_i32 s52, s0, 0x1600000
	s_add_u32 s52, s52, 0xb008000
	v_mov_b32_e32 v29, 0x2000
	v_mov_b32_e32 v28, 0x2c00
	v_mad_u32_u24 v0, v30, v29, v31
	v_mad_u32_u24 v5, v26, v28, v27
	v_add_u32_e32 v1, 0x8000, v0
	v_add_u32_e32 v2, 0x10000, v0
	v_add_u32_e32 v3, 0x18000, v0
	s_barrier
	s_mov_b32 s41, 0
	s_mov_b32 s47, s40
	s_mov_b32 s48, s46
	s_mul_hi_u32 s0, s47, 0x2e8ba3
	s_mul_i32 s1, s0, 1408
	s_sub_u32 s1, s47, s1
	s_mul_hi_u32 s2, s1, 0x8000001
	s_mul_i32 s8, s2, 32
	s_sub_u32 s8, s1, s8
	s_mul_i32 s9, s0, 0x2c00000
	s_mul_i32 s28, s2, 0x100000
	s_add_u32 s9, s9, s28
	s_lshl_b32 s8, s8, 8
	s_add_u32 s9, s9, s8
	s_add_u32 s42, s50, s9
	s_addc_u32 s43, s51, 0
	s_mov_b32 m0, s48
	s_add_u32 s49, s48, 0x400
	global_load_lds_dwordx4 v0, s[42:43] nt
	s_mov_b32 m0, s49
	s_add_u32 s49, s48, 0x800
	global_load_lds_dwordx4 v1, s[42:43] nt
	s_mov_b32 m0, s49
	s_add_u32 s49, s48, 0xc00
	global_load_lds_dwordx4 v2, s[42:43] nt
	s_mov_b32 m0, s49
	s_nop 0
	global_load_lds_dwordx4 v3, s[42:43] nt
	global_load_dword v24, v173, s[74:75]
	global_load_dword v24, v173, s[74:75]
	s_add_u32 s47, s40, s98
	s_add_u32 s48, s46, 0x8000
	s_cmp_lt_u32 s47, 1408
	s_cbranch_scc0 .Ldf_ddown_pd1
	s_mul_hi_u32 s0, s47, 0x2e8ba3
	s_mul_i32 s1, s0, 1408
	s_sub_u32 s1, s47, s1
	s_mul_hi_u32 s2, s1, 0x8000001
	s_mul_i32 s8, s2, 32
	s_sub_u32 s8, s1, s8
	s_mul_i32 s9, s0, 0x2c00000
	s_mul_i32 s28, s2, 0x100000
	s_add_u32 s9, s9, s28
	s_lshl_b32 s8, s8, 8
	s_add_u32 s9, s9, s8
	s_add_u32 s42, s50, s9
	s_addc_u32 s43, s51, 0
	s_mov_b32 m0, s48
	s_add_u32 s49, s48, 0x400
	global_load_lds_dwordx4 v0, s[42:43] nt
	s_mov_b32 m0, s49
	s_add_u32 s49, s48, 0x800
	global_load_lds_dwordx4 v1, s[42:43] nt
	s_mov_b32 m0, s49
	s_add_u32 s49, s48, 0xc00
	global_load_lds_dwordx4 v2, s[42:43] nt
	s_mov_b32 m0, s49
	s_nop 0
	global_load_lds_dwordx4 v3, s[42:43] nt
	s_branch .Ldf_ddown_pj1

; #define CVT_LOAD(tile_) do { const int k0_ = ((tile_) / ntn) << 7, n0_ = ((tile_) % ntn) << 6; \
;         _Pragma("unroll") for (int pp = 0; pp < 4; ++pp) pv[pp] = *(const float4*)(src + (size_t)(k0_ + lk + 32 * pp) * N + n0_ + ln4); } while (0)
; __device__ __forceinline__ void convT_job(const float* __restrict__ src, bf16_t* __restrict__ dst, int K, int N, int mode, float* t) {
;     ...
;         if (tile + (int)gridDim.x < ntiles) CVT_LOAD(tile + (int)gridDim.x);
.Ldf_ddown_pj1:
	global_load_dword v24, v173, s[74:75]
	global_load_dword v24, v173, s[74:75]
	s_lshl_b32 s47, s98, 1
	s_add_u32 s47, s47, s40
	s_add_u32 s48, s46, 0x10000
	s_cmp_lt_u32 s47, 1408
	s_cbranch_scc0 .Ldf_ddown_pd2
	s_mul_hi_u32 s0, s47, 0x2e8ba3
	s_mul_i32 s1, s0, 1408
	s_sub_u32 s1, s47, s1
	s_mul_hi_u32 s2, s1, 0x8000001
	s_mul_i32 s8, s2, 32
	s_sub_u32 s8, s1, s8
	s_mul_i32 s9, s0, 0x2c00000
	s_mul_i32 s28, s2, 0x100000
	s_add_u32 s9, s9, s28
	s_lshl_b32 s8, s8, 8
	s_add_u32 s9, s9, s8
	s_add_u32 s42, s50, s9
	s_addc_u32 s43, s51, 0
	s_mov_b32 m0, s48
	s_add_u32 s49, s48, 0x400
	global_load_lds_dwordx4 v0, s[42:43] nt
	s_mov_b32 m0, s49
	s_add_u32 s49, s48, 0x800
	global_load_lds_dwordx4 v1, s[42:43] nt
	s_mov_b32 m0, s49
	s_add_u32 s49, s48, 0xc00
	global_load_lds_dwordx4 v2, s[42:43] nt
	s_mov_b32 m0, s49
	s_nop 0
	global_load_lds_dwordx4 v3, s[42:43] nt
	s_branch .Ldf_ddown_pj2

; #define CVT_LOAD(tile_) do { const int k0_ = ((tile_) / ntn) << 7, n0_ = ((tile_) % ntn) << 6; \
;         _Pragma("unroll") for (int pp = 0; pp < 4; ++pp) pv[pp] = *(const float4*)(src + (size_t)(k0_ + lk + 32 * pp) * N + n0_ + ln4); } while (0)
; __device__ __forceinline__ void convT_job(const float* __restrict__ src, bf16_t* __restrict__ dst, int K, int N, int mode, float* t) {
;     ...
; #pragma unroll 1
;     for (; tile < ntiles; tile += gridDim.x) {
;         const int k0 = (tile / ntn) << 7, n0 = (tile % ntn) << 6;
; #pragma unroll
;         for (int pp = 0; pp < 4; ++pp) { const int k = lk + 32 * pp; t[k * 65 + ln4] = pv[pp].x; t[k * 65 + ln4 + 1] = pv[pp].y; t[k * 65 + ln4 + 2] = pv[pp].z; t[k * 65 + ln4 + 3] = pv[pp].w; }
;         if (tile + (int)gridDim.x < ntiles) CVT_LOAD(tile + (int)gridDim.x);
.Ldf_ddown_loop:
	s_waitcnt vmcnt(14)
	s_barrier
	s_mul_i32 s47, s98, 3
	s_add_u32 s47, s47, s40
	s_add_u32 s48, s41, 0x18000
	s_and_b32 s48, s48, 0x1ffff
	s_add_u32 s48, s48, s46
	s_cmp_lt_u32 s47, 1408
	s_cbranch_scc0 .Ldf_ddown_ld
	s_mul_hi_u32 s0, s47, 0x2e8ba3
	s_mul_i32 s1, s0, 1408
	s_sub_u32 s1, s47, s1
	s_mul_hi_u32 s2, s1, 0x8000001
	s_mul_i32 s8, s2, 32
	s_sub_u32 s8, s1, s8
	s_mul_i32 s9, s0, 0x2c00000
	s_mul_i32 s28, s2, 0x100000
	s_add_u32 s9, s9, s28
	s_lshl_b32 s8, s8, 8
	s_add_u32 s9, s9, s8
	s_add_u32 s42, s50, s9
	s_addc_u32 s43, s51, 0
	s_mov_b32 m0, s48
	s_add_u32 s49, s48, 0x400
	global_load_lds_dwordx4 v0, s[42:43] nt
	s_mov_b32 m0, s49
	s_add_u32 s49, s48, 0x800
	global_load_lds_dwordx4 v1, s[42:43] nt
	s_mov_b32 m0, s49
	s_add_u32 s49, s48, 0xc00
	global_load_lds_dwordx4 v2, s[42:43] nt
	s_mov_b32 m0, s49
	s_nop 0
	global_load_lds_dwordx4 v3, s[42:43] nt
	s_branch .Ldf_ddown_lj

; __device__ __forceinline__ unsigned cvt_pk_bf16(float lo, float hi) { unsigned r; asm volatile("v_cvt_pk_bf16_f32 %0, %1, %2" : "=v"(r) : "v"(lo), "v"(hi)); return r; }
; __device__ __forceinline__ void lds_barrier() { asm volatile("s_waitcnt lgkmcnt(0)" ::: "memory"); __builtin_amdgcn_s_barrier(); asm volatile("" ::: "memory"); }
; __device__ __forceinline__ void convT_job(const float* __restrict__ src, bf16_t* __restrict__ dst, int K, int N, int mode, float* t) {
;     ...
;         lds_barrier();
;         const int n = tid >> 3, k16 = (tid & 7) * 16;
;         float v[16];
; #pragma unroll
;         for (int j = 0; j < 16; ++j) v[j] = t[(k16 + j) * 65 + n];
;         const int nn = n0 + n;
;         const int row = mode == 0 ? nn : (256 * (nn >> 7) + (nn & 127) + (mode == 2 ? 128 : 0));
;         u32x4 w0, w1; w0.x = cvt_pk_bf16(v[0], v[1]); w0.y = cvt_pk_bf16(v[2], v[3]); w0.z = cvt_pk_bf16(v[4], v[5]); w0.w = cvt_pk_bf16(v[6], v[7]);
;         w1.x = cvt_pk_bf16(v[8], v[9]); w1.y = cvt_pk_bf16(v[10], v[11]); w1.z = cvt_pk_bf16(v[12], v[13]); w1.w = cvt_pk_bf16(v[14], v[15]);
;         bf16_t* d = dst + (size_t)row * K + k0 + k16;
;         *(u32x4*)d = w0; *(u32x4*)(d + 8) = w1;
;         lds_barrier();
; __device__ __forceinline__ void phase_convert(const Params& p, unsigned char* smem) {
;     ...
;         convT_job(p.in[7] + (size_t)l * 2048 * 2048, (bf16_t*)(p.ws + OFF_OUT + (size_t)l * SZ_OUT), 2048, 2048, 0, t);
.Ldf_ddown_lj:
	v_add_u32_e32 v7, s41, v4
	ds_read2st64_b32 v[8:9], v7 offset0:0 offset1:1
	ds_read2st64_b32 v[10:11], v7 offset0:2 offset1:3
	ds_read2st64_b32 v[12:13], v7 offset0:4 offset1:5
	ds_read2st64_b32 v[14:15], v7 offset0:6 offset1:7
	ds_read2st64_b32 v[16:17], v7 offset0:8 offset1:9
	ds_read2st64_b32 v[18:19], v7 offset0:10 offset1:11
	ds_read2st64_b32 v[20:21], v7 offset0:12 offset1:13
	ds_read2st64_b32 v[22:23], v7 offset0:14 offset1:15
	s_mul_hi_u32 s0, s40, 0x2e8ba3
	s_mul_i32 s1, s0, 1408
	s_sub_u32 s1, s40, s1
	s_mul_hi_u32 s2, s1, 0x8000001
	s_mul_i32 s8, s2, 32
	s_sub_u32 s8, s1, s8
	s_lshl_b32 s9, s8, 6
	s_mul_i32 s9, s9, 0x2c00
	s_mul_i32 s28, s0, 0x1600000
	s_add_u32 s9, s9, s28
	s_lshl_b32 s2, s2, 8
	s_add_u32 s9, s9, s2
	s_add_u32 s9, s9, s52
	s_add_u32 s44, s54, s9
	s_addc_u32 s45, s55, 0
	s_waitcnt lgkmcnt(6)
	v_cvt_pk_bf16_f32 v8, v8, v9
	v_cvt_pk_bf16_f32 v9, v10, v11
	s_waitcnt lgkmcnt(4)
	v_cvt_pk_bf16_f32 v10, v12, v13
	v_cvt_pk_bf16_f32 v11, v14, v15
	s_waitcnt lgkmcnt(2)
	v_cvt_pk_bf16_f32 v12, v16, v17
	v_cvt_pk_bf16_f32 v13, v18, v19
	s_waitcnt lgkmcnt(0)
	v_cvt_pk_bf16_f32 v14, v20, v21
	v_cvt_pk_bf16_f32 v15, v22, v23
	global_store_dwordx4 v5, v[8:11], s[44:45]
	global_store_dwordx4 v5, v[12:15], s[44:45] offset:16
	s_add_u32 s40, s40, s98
	s_add_u32 s41, s41, 0x8000
	s_and_b32 s41, s41, 0x1ffff
	s_cmp_lt_u32 s40, 1408
	s_cbranch_scc1 .Ldf_ddown_loop
.Ldf_ddown_skip:
	s_sub_u32 s40, s60, s99
	s_cmp_lt_u32 s40, 512
	s_cbranch_scc0 .Ldf_dwout_skip
	s_mul_i32 s0, s53, 1
	s_mul_hi_u32 s1, s0, 0x1000000
	s_mul_i32 s2, s0, 0x1000000
	s_add_u32 s50, s78, s2
	s_addc_u32 s51, s79, s1
	s_mul_i32 s52, s0, 0x800000
	s_add_u32 s52, s52, 0x13408000
	v_mov_b32_e32 v29, 0x2000
	v_mov_b32_e32 v28, 0x1000
	v_mad_u32_u24 v0, v30, v29, v31
	v_mad_u32_u24 v5, v26, v28, v27
	v_add_u32_e32 v1, 0x8000, v0
	v_add_u32_e32 v2, 0x10000, v0
	v_add_u32_e32 v3, 0x18000, v0
	s_barrier
	s_mov_b32 s41, 0
	s_mov_b32 s47, s40
	s_mov_b32 s48, s46
	s_mul_hi_u32 s0, s47, 0x800001
	s_mul_i32 s1, s0, 512
	s_sub_u32 s1, s47, s1
	s_mul_hi_u32 s2, s1, 0x8000001
	s_mul_i32 s8, s2, 32
	s_sub_u32 s8, s1, s8
	s_mul_i32 s9, s0, 0x1000000
	s_mul_i32 s28, s2, 0x100000
	s_add_u32 s9, s9, s28
	s_lshl_b32 s8, s8, 8
	s_add_u32 s9, s9, s8
	s_add_u32 s42, s50, s9
	s_addc_u32 s43, s51, 0
	s_mov_b32 m0, s48
	s_add_u32 s49, s48, 0x400
	global_load_lds_dwordx4 v0, s[42:43] nt
	s_mov_b32 m0, s49
	s_add_u32 s49, s48, 0x800
	global_load_lds_dwordx4 v1, s[42:43] nt
	s_mov_b32 m0, s49
	s_add_u32 s49, s48, 0xc00
	global_load_lds_dwordx4 v2, s[42:43] nt
	s_mov_b32 m0, s49
	s_nop 0
	global_load_lds_dwordx4 v3, s[42:43] nt
	global_load_dword v24, v173, s[78:79]
	global_load_dword v24, v173, s[78:79]
	s_add_u32 s47, s40, s98
	s_add_u32 s48, s46, 0x8000
	s_cmp_lt_u32 s47, 512
	s_cbranch_scc0 .Ldf_dwout_pd1
	s_mul_hi_u32 s0, s47, 0x800001
	s_mul_i32 s1, s0, 512
	s_sub_u32 s1, s47, s1
	s_mul_hi_u32 s2, s1, 0x8000001
	s_mul_i32 s8, s2, 32
	s_sub_u32 s8, s1, s8
	s_mul_i32 s9, s0, 0x1000000
	s_mul_i32 s28, s2, 0x100000
	s_add_u32 s9, s9, s28
	s_lshl_b32 s8, s8, 8
	s_add_u32 s9, s9, s8
	s_add_u32 s42, s50, s9
	s_addc_u32 s43, s51, 0
	s_mov_b32 m0, s48
	s_add_u32 s49, s48, 0x400
	global_load_lds_dwordx4 v0, s[42:43] nt
	s_mov_b32 m0, s49
	s_add_u32 s49, s48, 0x800
	global_load_lds_dwordx4 v1, s[42:43] nt
	s_mov_b32 m0, s49
	s_add_u32 s49, s48, 0xc00
	global_load_lds_dwordx4 v2, s[42:43] nt
	s_mov_b32 m0, s49
	s_nop 0
	global_load_lds_dwordx4 v3, s[42:43] nt
	s_branch .Ldf_dwout_pj1

; #define CVT_LOAD(tile_) do { const int k0_ = ((tile_) / ntn) << 7, n0_ = ((tile_) % ntn) << 6; \
;         _Pragma("unroll") for (int pp = 0; pp < 4; ++pp) pv[pp] = *(const float4*)(src + (size_t)(k0_ + lk + 32 * pp) * N + n0_ + ln4); } while (0)
; __device__ __forceinline__ void convT_job(const float* __restrict__ src, bf16_t* __restrict__ dst, int K, int N, int mode, float* t) {
;     ...
;         if (tile + (int)gridDim.x < ntiles) CVT_LOAD(tile + (int)gridDim.x);
.Ldf_dwout_pj1:
	global_load_dword v24, v173, s[78:79]
	global_load_dword v24, v173, s[78:79]
	s_lshl_b32 s47, s98, 1
	s_add_u32 s47, s47, s40
	s_add_u32 s48, s46, 0x10000
	s_cmp_lt_u32 s47, 512
	s_cbranch_scc0 .Ldf_dwout_pd2
	s_mul_hi_u32 s0, s47, 0x800001
	s_mul_i32 s1, s0, 512
	s_sub_u32 s1, s47, s1
	s_mul_hi_u32 s2, s1, 0x8000001
	s_mul_i32 s8, s2, 32
	s_sub_u32 s8, s1, s8
	s_mul_i32 s9, s0, 0x1000000
	s_mul_i32 s28, s2, 0x100000
	s_add_u32 s9, s9, s28
	s_lshl_b32 s8, s8, 8
	s_add_u32 s9, s9, s8
	s_add_u32 s42, s50, s9
	s_addc_u32 s43, s51, 0
	s_mov_b32 m0, s48
	s_add_u32 s49, s48, 0x400
	global_load_lds_dwordx4 v0, s[42:43] nt
	s_mov_b32 m0, s49
	s_add_u32 s49, s48, 0x800
	global_load_lds_dwordx4 v1, s[42:43] nt
	s_mov_b32 m0, s49
	s_add_u32 s49, s48, 0xc00
	global_load_lds_dwordx4 v2, s[42:43] nt
	s_mov_b32 m0, s49
	s_nop 0
	global_load_lds_dwordx4 v3, s[42:43] nt
	s_branch .Ldf_dwout_pj2

; #define CVT_LOAD(tile_) do { const int k0_ = ((tile_) / ntn) << 7, n0_ = ((tile_) % ntn) << 6; \
;         _Pragma("unroll") for (int pp = 0; pp < 4; ++pp) pv[pp] = *(const float4*)(src + (size_t)(k0_ + lk + 32 * pp) * N + n0_ + ln4); } while (0)
; __device__ __forceinline__ void convT_job(const float* __restrict__ src, bf16_t* __restrict__ dst, int K, int N, int mode, float* t) {
;     ...
; #pragma unroll 1
;     for (; tile < ntiles; tile += gridDim.x) {
;         const int k0 = (tile / ntn) << 7, n0 = (tile % ntn) << 6;
; #pragma unroll
;         for (int pp = 0; pp < 4; ++pp) { const int k = lk + 32 * pp; t[k * 65 + ln4] = pv[pp].x; t[k * 65 + ln4 + 1] = pv[pp].y; t[k * 65 + ln4 + 2] = pv[pp].z; t[k * 65 + ln4 + 3] = pv[pp].w; }
;         if (tile + (int)gridDim.x < ntiles) CVT_LOAD(tile + (int)gridDim.x);
.Ldf_dwout_loop:
	s_waitcnt vmcnt(14)
	s_barrier
	s_mul_i32 s47, s98, 3
	s_add_u32 s47, s47, s40
	s_add_u32 s48, s41, 0x18000
	s_and_b32 s48, s48, 0x1ffff
	s_add_u32 s48, s48, s46
	s_cmp_lt_u32 s47, 512
	s_cbranch_scc0 .Ldf_dwout_ld
	s_mul_hi_u32 s0, s47, 0x800001
	s_mul_i32 s1, s0, 512
	s_sub_u32 s1, s47, s1
	s_mul_hi_u32 s2, s1, 0x8000001
	s_mul_i32 s8, s2, 32
	s_sub_u32 s8, s1, s8
	s_mul_i32 s9, s0, 0x1000000
	s_mul_i32 s28, s2, 0x100000
	s_add_u32 s9, s9, s28
	s_lshl_b32 s8, s8, 8
	s_add_u32 s9, s9, s8
	s_add_u32 s42, s50, s9
	s_addc_u32 s43, s51, 0
	s_mov_b32 m0, s48
	s_add_u32 s49, s48, 0x400
	global_load_lds_dwordx4 v0, s[42:43] nt
	s_mov_b32 m0, s49
	s_add_u32 s49, s48, 0x800
	global_load_lds_dwordx4 v1, s[42:43] nt
	s_mov_b32 m0, s49
	s_add_u32 s49, s48, 0xc00
	global_load_lds_dwordx4 v2, s[42:43] nt
	s_mov_b32 m0, s49
	s_nop 0
	global_load_lds_dwordx4 v3, s[42:43] nt
	s_branch .Ldf_dwout_lj

; __device__ __forceinline__ unsigned cvt_pk_bf16(float lo, float hi) { unsigned r; asm volatile("v_cvt_pk_bf16_f32 %0, %1, %2" : "=v"(r) : "v"(lo), "v"(hi)); return r; }
; __device__ __forceinline__ void lds_barrier() { asm volatile("s_waitcnt lgkmcnt(0)" ::: "memory"); __builtin_amdgcn_s_barrier(); asm volatile("" ::: "memory"); }
; __device__ __forceinline__ void convT_job(const float* __restrict__ src, bf16_t* __restrict__ dst, int K, int N, int mode, float* t) {
;     ...
;         const int n = tid >> 3, k16 = (tid & 7) * 16;
;         float v[16];
; #pragma unroll
;         for (int j = 0; j < 16; ++j) v[j] = t[(k16 + j) * 65 + n];
;         const int nn = n0 + n;
;         const int row = mode == 0 ? nn : (256 * (nn >> 7) + (nn & 127) + (mode == 2 ? 128 : 0));
;         u32x4 w0, w1; w0.x = cvt_pk_bf16(v[0], v[1]); w0.y = cvt_pk_bf16(v[2], v[3]); w0.z = cvt_pk_bf16(v[4], v[5]); w0.w = cvt_pk_bf16(v[6], v[7]);
;         w1.x = cvt_pk_bf16(v[8], v[9]); w1.y = cvt_pk_bf16(v[10], v[11]); w1.z = cvt_pk_bf16(v[12], v[13]); w1.w = cvt_pk_bf16(v[14], v[15]);
;         bf16_t* d = dst + (size_t)row * K + k0 + k16;
;         *(u32x4*)d = w0; *(u32x4*)(d + 8) = w1;
;         lds_barrier();
.Ldf_dwout_lj:
	v_add_u32_e32 v7, s41, v4
	ds_read2st64_b32 v[8:9], v7 offset0:0 offset1:1
	ds_read2st64_b32 v[10:11], v7 offset0:2 offset1:3
	ds_read2st64_b32 v[12:13], v7 offset0:4 offset1:5
	ds_read2st64_b32 v[14:15], v7 offset0:6 offset1:7
	ds_read2st64_b32 v[16:17], v7 offset0:8 offset1:9
	ds_read2st64_b32 v[18:19], v7 offset0:10 offset1:11
	ds_read2st64_b32 v[20:21], v7 offset0:12 offset1:13
	ds_read2st64_b32 v[22:23], v7 offset0:14 offset1:15
	s_mul_hi_u32 s0, s40, 0x800001
	s_mul_i32 s1, s0, 512
	s_sub_u32 s1, s40, s1
	s_mul_hi_u32 s2, s1, 0x8000001
	s_mul_i32 s8, s2, 32
	s_sub_u32 s8, s1, s8
	s_lshl_b32 s9, s8, 6
	s_mul_i32 s9, s9, 0x1000
	s_mul_i32 s28, s0, 0x800000
	s_add_u32 s9, s9, s28
	s_lshl_b32 s2, s2, 8
	s_add_u32 s9, s9, s2
	s_add_u32 s9, s9, s52
	s_add_u32 s44, s54, s9
	s_addc_u32 s45, s55, 0
	s_waitcnt lgkmcnt(6)
	v_cvt_pk_bf16_f32 v8, v8, v9
	v_cvt_pk_bf16_f32 v9, v10, v11
	s_waitcnt lgkmcnt(4)
	v_cvt_pk_bf16_f32 v10, v12, v13
	v_cvt_pk_bf16_f32 v11, v14, v15
	s_waitcnt lgkmcnt(2)
	v_cvt_pk_bf16_f32 v12, v16, v17
	v_cvt_pk_bf16_f32 v13, v18, v19
	s_waitcnt lgkmcnt(0)
	v_cvt_pk_bf16_f32 v14, v20, v21
	v_cvt_pk_bf16_f32 v15, v22, v23
	global_store_dwordx4 v5, v[8:11], s[44:45]
	global_store_dwordx4 v5, v[12:15], s[44:45] offset:16
	s_add_u32 s40, s40, s98
	s_add_u32 s41, s41, 0x8000
	s_and_b32 s41, s41, 0x1ffff
	s_cmp_lt_u32 s40, 512
	s_cbranch_scc1 .Ldf_dwout_loop

; __device__ __forceinline__ int opaque_tid() { int t = threadIdx.x; asm volatile("" : "+v"(t)); return t; }
; #define CVT_LOAD(tile_) do { const int k0_ = ((tile_) / ntn) << 7, n0_ = ((tile_) % ntn) << 6; \
;         _Pragma("unroll") for (int pp = 0; pp < 4; ++pp) pv[pp] = *(const float4*)(src + (size_t)(k0_ + lk + 32 * pp) * N + n0_ + ln4); } while (0)
; __device__ __forceinline__ void convT_job(const float* __restrict__ src, bf16_t* __restrict__ dst, int K, int N, int mode, float* t) {
;     const int tid = opaque_tid(), ntn = N >> 6, ntiles = (K >> 7) * ntn;
;     const int lk = tid >> 4, ln4 = (tid & 15) * 4;
;     float4 pv[4];
;     ...
;     int tile = blockIdx.x;
;     if (tile < ntiles) CVT_LOAD(tile);
; __device__ __forceinline__ void phase_convert(const Params& p, unsigned char* smem) {
;     ...
;     for (int l = 0; l < 2; ++l) {
;         for (int f = 0; f < 2; ++f) {
;             const size_t wo = (size_t)(l * 2 + f) * 2048 * 5632;
;             bf16_t* gu = (bf16_t*)(p.ws + OFF_GU + (size_t)(l * 2 + f) * SZ_GU);
;             convT_job(p.in[3] + wo, gu, 2048, 5632, 1, t);
.LBB0_623:
	s_load_dword s98, s[96:97], 0x0
	v_lshrrev_b32_e32 v6, 6, v234
	v_and_b32_e32 v25, 63, v234
	v_lshrrev_b32_e32 v26, 3, v234
	v_readfirstlane_b32 s46, v6
	v_and_b32_e32 v27, 7, v234
	v_readlane_b32 s54, v255, 28
	v_readlane_b32 s55, v255, 29
	s_lshl_b32 s46, s46, 12
	v_lshrrev_b32_e32 v28, 2, v26
	v_xor_b32_e32 v28, v28, v27
	v_lshlrev_b32_e32 v28, 4, v28
	v_and_b32_e32 v29, 3, v26
	v_lshl_or_b32 v28, v29, 2, v28
	v_lshl_or_b32 v4, v27, 12, v28
	v_lshrrev_b32_e32 v30, 4, v25
	v_lshl_add_u32 v30, v6, 4, v30
	v_and_b32_e32 v31, 15, v25
	v_xor_b32_e32 v31, v31, v6
	v_lshlrev_b32_e32 v31, 4, v31
	v_lshlrev_b32_e32 v27, 5, v27
	s_waitcnt lgkmcnt(0)
	s_mov_b32 s40, s60
	s_cmp_lt_u32 s40, 2816
	s_cbranch_scc0 .Lcv_gate_skip
	v_mov_b32_e32 v29, 0x5800
	v_mov_b32_e32 v28, 0x1000
	v_mad_u32_u24 v0, v30, v29, v31
	v_mad_u32_u24 v5, v26, v28, v27
	v_add_u32_e32 v1, 0x16000, v0
	v_add_u32_e32 v2, 0x2c000, v0
	v_add_u32_e32 v3, 0x42000, v0
	s_barrier
	s_mov_b32 s41, 0
	s_mov_b32 s47, s40
	s_mov_b32 s48, s46
	s_mul_hi_u32 s0, s47, 0x2e8ba3
	s_mul_i32 s1, s0, 1408
	s_sub_u32 s1, s47, s1
	s_mul_hi_u32 s2, s1, 0x2e8ba2f
	s_mul_i32 s8, s2, 88
	s_sub_u32 s8, s1, s8
	s_mul_i32 s9, s0, 0x5800000
	s_mul_i32 s28, s2, 0x2c0000
	s_add_u32 s9, s9, s28
	s_lshl_b32 s8, s8, 8
	s_add_u32 s9, s9, s8
	s_add_u32 s42, s70, s9
	s_addc_u32 s43, s71, 0
	s_mov_b32 m0, s48
	s_add_u32 s49, s48, 0x400
	global_load_lds_dwordx4 v0, s[42:43] nt
	s_mov_b32 m0, s49
	s_add_u32 s49, s48, 0x800
	global_load_lds_dwordx4 v1, s[42:43] nt
	s_mov_b32 m0, s49
	s_add_u32 s49, s48, 0xc00
	global_load_lds_dwordx4 v2, s[42:43] nt
	s_mov_b32 m0, s49
	s_nop 0
	global_load_lds_dwordx4 v3, s[42:43] nt
	global_load_dword v24, v173, s[70:71]
	global_load_dword v24, v173, s[70:71]
	s_add_u32 s47, s40, s98
	s_add_u32 s48, s46, 0x8000
	s_cmp_lt_u32 s47, 2816
	s_cbranch_scc0 .Lcv_gate_pd1
	s_mul_hi_u32 s0, s47, 0x2e8ba3
	s_mul_i32 s1, s0, 1408
	s_sub_u32 s1, s47, s1
	s_mul_hi_u32 s2, s1, 0x2e8ba2f
	s_mul_i32 s8, s2, 88
	s_sub_u32 s8, s1, s8
	s_mul_i32 s9, s0, 0x5800000
	s_mul_i32 s28, s2, 0x2c0000
	s_add_u32 s9, s9, s28
	s_lshl_b32 s8, s8, 8
	s_add_u32 s9, s9, s8
	s_add_u32 s42, s70, s9
	s_addc_u32 s43, s71, 0
	s_mov_b32 m0, s48
	s_add_u32 s49, s48, 0x400
	global_load_lds_dwordx4 v0, s[42:43] nt
	s_mov_b32 m0, s49
	s_add_u32 s49, s48, 0x800
	global_load_lds_dwordx4 v1, s[42:43] nt
	s_mov_b32 m0, s49
	s_add_u32 s49, s48, 0xc00
	global_load_lds_dwordx4 v2, s[42:43] nt
	s_mov_b32 m0, s49
	s_nop 0
	global_load_lds_dwordx4 v3, s[42:43] nt
	s_branch .Lcv_gate_pj1

; #define CVT_LOAD(tile_) do { const int k0_ = ((tile_) / ntn) << 7, n0_ = ((tile_) % ntn) << 6; \
;         _Pragma("unroll") for (int pp = 0; pp < 4; ++pp) pv[pp] = *(const float4*)(src + (size_t)(k0_ + lk + 32 * pp) * N + n0_ + ln4); } while (0)
; __device__ __forceinline__ void convT_job(const float* __restrict__ src, bf16_t* __restrict__ dst, int K, int N, int mode, float* t) {
;     ...
;         if (tile + (int)gridDim.x < ntiles) CVT_LOAD(tile + (int)gridDim.x);
.Lcv_gate_pj1:
	global_load_dword v24, v173, s[70:71]
	global_load_dword v24, v173, s[70:71]
	s_lshl_b32 s47, s98, 1
	s_add_u32 s47, s47, s40
	s_add_u32 s48, s46, 0x10000
	s_cmp_lt_u32 s47, 2816
	s_cbranch_scc0 .Lcv_gate_pd2
	s_mul_hi_u32 s0, s47, 0x2e8ba3
	s_mul_i32 s1, s0, 1408
	s_sub_u32 s1, s47, s1
	s_mul_hi_u32 s2, s1, 0x2e8ba2f
	s_mul_i32 s8, s2, 88
	s_sub_u32 s8, s1, s8
	s_mul_i32 s9, s0, 0x5800000
	s_mul_i32 s28, s2, 0x2c0000
	s_add_u32 s9, s9, s28
	s_lshl_b32 s8, s8, 8
	s_add_u32 s9, s9, s8
	s_add_u32 s42, s70, s9
	s_addc_u32 s43, s71, 0
	s_mov_b32 m0, s48
	s_add_u32 s49, s48, 0x400
	global_load_lds_dwordx4 v0, s[42:43] nt
	s_mov_b32 m0, s49
	s_add_u32 s49, s48, 0x800
	global_load_lds_dwordx4 v1, s[42:43] nt
	s_mov_b32 m0, s49
	s_add_u32 s49, s48, 0xc00
	global_load_lds_dwordx4 v2, s[42:43] nt
	s_mov_b32 m0, s49
	s_nop 0
	global_load_lds_dwordx4 v3, s[42:43] nt
	s_branch .Lcv_gate_pj2

; #define CVT_LOAD(tile_) do { const int k0_ = ((tile_) / ntn) << 7, n0_ = ((tile_) % ntn) << 6; \
;         _Pragma("unroll") for (int pp = 0; pp < 4; ++pp) pv[pp] = *(const float4*)(src + (size_t)(k0_ + lk + 32 * pp) * N + n0_ + ln4); } while (0)
; __device__ __forceinline__ void convT_job(const float* __restrict__ src, bf16_t* __restrict__ dst, int K, int N, int mode, float* t) {
;     ...
; #pragma unroll 1
;     for (; tile < ntiles; tile += gridDim.x) {
;         const int k0 = (tile / ntn) << 7, n0 = (tile % ntn) << 6;
; #pragma unroll
;         for (int pp = 0; pp < 4; ++pp) { const int k = lk + 32 * pp; t[k * 65 + ln4] = pv[pp].x; t[k * 65 + ln4 + 1] = pv[pp].y; t[k * 65 + ln4 + 2] = pv[pp].z; t[k * 65 + ln4 + 3] = pv[pp].w; }
;         if (tile + (int)gridDim.x < ntiles) CVT_LOAD(tile + (int)gridDim.x);
.Lcv_gate_loop:
	s_waitcnt vmcnt(14)
	s_barrier
	s_mul_i32 s47, s98, 3
	s_add_u32 s47, s47, s40
	s_add_u32 s48, s41, 0x18000
	s_and_b32 s48, s48, 0x1ffff
	s_add_u32 s48, s48, s46
	s_cmp_lt_u32 s47, 2816
	s_cbranch_scc0 .Lcv_gate_ld
	s_mul_hi_u32 s0, s47, 0x2e8ba3
	s_mul_i32 s1, s0, 1408
	s_sub_u32 s1, s47, s1
	s_mul_hi_u32 s2, s1, 0x2e8ba2f
	s_mul_i32 s8, s2, 88
	s_sub_u32 s8, s1, s8
	s_mul_i32 s9, s0, 0x5800000
	s_mul_i32 s28, s2, 0x2c0000
	s_add_u32 s9, s9, s28
	s_lshl_b32 s8, s8, 8
	s_add_u32 s9, s9, s8
	s_add_u32 s42, s70, s9
	s_addc_u32 s43, s71, 0
	s_mov_b32 m0, s48
	s_add_u32 s49, s48, 0x400
	global_load_lds_dwordx4 v0, s[42:43] nt
	s_mov_b32 m0, s49
	s_add_u32 s49, s48, 0x800
	global_load_lds_dwordx4 v1, s[42:43] nt
	s_mov_b32 m0, s49
	s_add_u32 s49, s48, 0xc00
	global_load_lds_dwordx4 v2, s[42:43] nt
	s_mov_b32 m0, s49
	s_nop 0
	global_load_lds_dwordx4 v3, s[42:43] nt
	s_branch .Lcv_gate_lj

; __device__ __forceinline__ unsigned cvt_pk_bf16(float lo, float hi) { unsigned r; asm volatile("v_cvt_pk_bf16_f32 %0, %1, %2" : "=v"(r) : "v"(lo), "v"(hi)); return r; }
; __device__ __forceinline__ void lds_barrier() { asm volatile("s_waitcnt lgkmcnt(0)" ::: "memory"); __builtin_amdgcn_s_barrier(); asm volatile("" ::: "memory"); }
; __device__ __forceinline__ void convT_job(const float* __restrict__ src, bf16_t* __restrict__ dst, int K, int N, int mode, float* t) {
;     ...
;         lds_barrier();
;         const int n = tid >> 3, k16 = (tid & 7) * 16;
;         float v[16];
; #pragma unroll
;         for (int j = 0; j < 16; ++j) v[j] = t[(k16 + j) * 65 + n];
;         const int nn = n0 + n;
;         const int row = mode == 0 ? nn : (256 * (nn >> 7) + (nn & 127) + (mode == 2 ? 128 : 0));
;         u32x4 w0, w1; w0.x = cvt_pk_bf16(v[0], v[1]); w0.y = cvt_pk_bf16(v[2], v[3]); w0.z = cvt_pk_bf16(v[4], v[5]); w0.w = cvt_pk_bf16(v[6], v[7]);
;         w1.x = cvt_pk_bf16(v[8], v[9]); w1.y = cvt_pk_bf16(v[10], v[11]); w1.z = cvt_pk_bf16(v[12], v[13]); w1.w = cvt_pk_bf16(v[14], v[15]);
;         bf16_t* d = dst + (size_t)row * K + k0 + k16;
;         *(u32x4*)d = w0; *(u32x4*)(d + 8) = w1;
;         lds_barrier();
; __device__ __forceinline__ void phase_convert(const Params& p, unsigned char* smem) {
;     ...
;             convT_job(p.in[3] + wo, gu, 2048, 5632, 1, t);
;             convT_job(p.in[4] + wo, gu, 2048, 5632, 2, t);
.Lcv_gate_lj:
	v_add_u32_e32 v7, s41, v4
	ds_read2st64_b32 v[8:9], v7 offset0:0 offset1:1
	ds_read2st64_b32 v[10:11], v7 offset0:2 offset1:3
	ds_read2st64_b32 v[12:13], v7 offset0:4 offset1:5
	ds_read2st64_b32 v[14:15], v7 offset0:6 offset1:7
	ds_read2st64_b32 v[16:17], v7 offset0:8 offset1:9
	ds_read2st64_b32 v[18:19], v7 offset0:10 offset1:11
	ds_read2st64_b32 v[20:21], v7 offset0:12 offset1:13
	ds_read2st64_b32 v[22:23], v7 offset0:14 offset1:15
	s_mul_hi_u32 s0, s40, 0x2e8ba3
	s_mul_i32 s1, s0, 1408
	s_sub_u32 s1, s40, s1
	s_mul_hi_u32 s2, s1, 0x2e8ba2f
	s_mul_i32 s8, s2, 88
	s_sub_u32 s8, s1, s8
	s_lshr_b32 s9, s8, 1
	s_lshl_b32 s9, s9, 8
	s_and_b32 s28, s8, 1
	s_lshl_b32 s28, s28, 6
	s_add_u32 s9, s9, s28
	s_mul_i32 s9, s9, 0x1000
	s_mul_i32 s28, s0, 0x5800000
	s_add_u32 s9, s9, s28
	s_lshl_b32 s2, s2, 8
	s_add_u32 s9, s9, s2
	s_add_u32 s9, s9, 0x8000
	s_add_u32 s44, s54, s9
	s_addc_u32 s45, s55, 0
	s_waitcnt lgkmcnt(6)
	v_cvt_pk_bf16_f32 v8, v8, v9
	v_cvt_pk_bf16_f32 v9, v10, v11
	s_waitcnt lgkmcnt(4)
	v_cvt_pk_bf16_f32 v10, v12, v13
	v_cvt_pk_bf16_f32 v11, v14, v15
	s_waitcnt lgkmcnt(2)
	v_cvt_pk_bf16_f32 v12, v16, v17
	v_cvt_pk_bf16_f32 v13, v18, v19
	s_waitcnt lgkmcnt(0)
	v_cvt_pk_bf16_f32 v14, v20, v21
	v_cvt_pk_bf16_f32 v15, v22, v23
	global_store_dwordx4 v5, v[8:11], s[44:45]
	global_store_dwordx4 v5, v[12:15], s[44:45] offset:16
	s_add_u32 s40, s40, s98
	s_add_u32 s41, s41, 0x8000
	s_and_b32 s41, s41, 0x1ffff
	s_cmp_lt_u32 s40, 2816
	s_cbranch_scc1 .Lcv_gate_loop
.Lcv_gate_skip:
	s_mov_b32 s40, s60
	s_cmp_lt_u32 s40, 2816
	s_cbranch_scc0 .Lcv_up_skip
	v_mov_b32_e32 v29, 0x5800
	v_mov_b32_e32 v28, 0x1000
	v_mad_u32_u24 v0, v30, v29, v31
	v_mad_u32_u24 v5, v26, v28, v27
	v_add_u32_e32 v1, 0x16000, v0
	v_add_u32_e32 v2, 0x2c000, v0
	v_add_u32_e32 v3, 0x42000, v0
	s_barrier
	s_mov_b32 s41, 0
	s_mov_b32 s47, s40
	s_mov_b32 s48, s46
	s_mul_hi_u32 s0, s47, 0x2e8ba3
	s_mul_i32 s1, s0, 1408
	s_sub_u32 s1, s47, s1
	s_mul_hi_u32 s2, s1, 0x2e8ba2f
	s_mul_i32 s8, s2, 88
	s_sub_u32 s8, s1, s8
	s_mul_i32 s9, s0, 0x5800000
	s_mul_i32 s28, s2, 0x2c0000
	s_add_u32 s9, s9, s28
	s_lshl_b32 s8, s8, 8
	s_add_u32 s9, s9, s8
	s_add_u32 s42, s72, s9
	s_addc_u32 s43, s73, 0
	s_mov_b32 m0, s48
	s_add_u32 s49, s48, 0x400
	global_load_lds_dwordx4 v0, s[42:43] nt
	s_mov_b32 m0, s49
	s_add_u32 s49, s48, 0x800
	global_load_lds_dwordx4 v1, s[42:43] nt
	s_mov_b32 m0, s49
	s_add_u32 s49, s48, 0xc00
	global_load_lds_dwordx4 v2, s[42:43] nt
	s_mov_b32 m0, s49
	s_nop 0
	global_load_lds_dwordx4 v3, s[42:43] nt
	global_load_dword v24, v173, s[72:73]
	global_load_dword v24, v173, s[72:73]
	s_add_u32 s47, s40, s98
	s_add_u32 s48, s46, 0x8000
	s_cmp_lt_u32 s47, 2816
	s_cbranch_scc0 .Lcv_up_pd1
	s_mul_hi_u32 s0, s47, 0x2e8ba3
	s_mul_i32 s1, s0, 1408
	s_sub_u32 s1, s47, s1
	s_mul_hi_u32 s2, s1, 0x2e8ba2f
	s_mul_i32 s8, s2, 88
	s_sub_u32 s8, s1, s8
	s_mul_i32 s9, s0, 0x5800000
	s_mul_i32 s28, s2, 0x2c0000
	s_add_u32 s9, s9, s28
	s_lshl_b32 s8, s8, 8
	s_add_u32 s9, s9, s8
	s_add_u32 s42, s72, s9
	s_addc_u32 s43, s73, 0
	s_mov_b32 m0, s48
	s_add_u32 s49, s48, 0x400
	global_load_lds_dwordx4 v0, s[42:43] nt
	s_mov_b32 m0, s49
	s_add_u32 s49, s48, 0x800
	global_load_lds_dwordx4 v1, s[42:43] nt
	s_mov_b32 m0, s49
	s_add_u32 s49, s48, 0xc00
	global_load_lds_dwordx4 v2, s[42:43] nt
	s_mov_b32 m0, s49
	s_nop 0
	global_load_lds_dwordx4 v3, s[42:43] nt
	s_branch .Lcv_up_pj1

; #define CVT_LOAD(tile_) do { const int k0_ = ((tile_) / ntn) << 7, n0_ = ((tile_) % ntn) << 6; \
;         _Pragma("unroll") for (int pp = 0; pp < 4; ++pp) pv[pp] = *(const float4*)(src + (size_t)(k0_ + lk + 32 * pp) * N + n0_ + ln4); } while (0)
; __device__ __forceinline__ void convT_job(const float* __restrict__ src, bf16_t* __restrict__ dst, int K, int N, int mode, float* t) {
;     ...
;         if (tile + (int)gridDim.x < ntiles) CVT_LOAD(tile + (int)gridDim.x);
.Lcv_up_pj1:
	global_load_dword v24, v173, s[72:73]
	global_load_dword v24, v173, s[72:73]
	s_lshl_b32 s47, s98, 1
	s_add_u32 s47, s47, s40
	s_add_u32 s48, s46, 0x10000
	s_cmp_lt_u32 s47, 2816
	s_cbranch_scc0 .Lcv_up_pd2
	s_mul_hi_u32 s0, s47, 0x2e8ba3
	s_mul_i32 s1, s0, 1408
	s_sub_u32 s1, s47, s1
	s_mul_hi_u32 s2, s1, 0x2e8ba2f
	s_mul_i32 s8, s2, 88
	s_sub_u32 s8, s1, s8
	s_mul_i32 s9, s0, 0x5800000
	s_mul_i32 s28, s2, 0x2c0000
	s_add_u32 s9, s9, s28
	s_lshl_b32 s8, s8, 8
	s_add_u32 s9, s9, s8
	s_add_u32 s42, s72, s9
	s_addc_u32 s43, s73, 0
	s_mov_b32 m0, s48
	s_add_u32 s49, s48, 0x400
	global_load_lds_dwordx4 v0, s[42:43] nt
	s_mov_b32 m0, s49
	s_add_u32 s49, s48, 0x800
	global_load_lds_dwordx4 v1, s[42:43] nt
	s_mov_b32 m0, s49
	s_add_u32 s49, s48, 0xc00
	global_load_lds_dwordx4 v2, s[42:43] nt
	s_mov_b32 m0, s49
	s_nop 0
	global_load_lds_dwordx4 v3, s[42:43] nt
	s_branch .Lcv_up_pj2

; #define CVT_LOAD(tile_) do { const int k0_ = ((tile_) / ntn) << 7, n0_ = ((tile_) % ntn) << 6; \
;         _Pragma("unroll") for (int pp = 0; pp < 4; ++pp) pv[pp] = *(const float4*)(src + (size_t)(k0_ + lk + 32 * pp) * N + n0_ + ln4); } while (0)
; __device__ __forceinline__ void convT_job(const float* __restrict__ src, bf16_t* __restrict__ dst, int K, int N, int mode, float* t) {
;     ...
; #pragma unroll 1
;     for (; tile < ntiles; tile += gridDim.x) {
;         const int k0 = (tile / ntn) << 7, n0 = (tile % ntn) << 6;
; #pragma unroll
;         for (int pp = 0; pp < 4; ++pp) { const int k = lk + 32 * pp; t[k * 65 + ln4] = pv[pp].x; t[k * 65 + ln4 + 1] = pv[pp].y; t[k * 65 + ln4 + 2] = pv[pp].z; t[k * 65 + ln4 + 3] = pv[pp].w; }
;         if (tile + (int)gridDim.x < ntiles) CVT_LOAD(tile + (int)gridDim.x);
.Lcv_up_loop:
	s_waitcnt vmcnt(14)
	s_barrier
	s_mul_i32 s47, s98, 3
	s_add_u32 s47, s47, s40
	s_add_u32 s48, s41, 0x18000
	s_and_b32 s48, s48, 0x1ffff
	s_add_u32 s48, s48, s46
	s_cmp_lt_u32 s47, 2816
	s_cbranch_scc0 .Lcv_up_ld
	s_mul_hi_u32 s0, s47, 0x2e8ba3
	s_mul_i32 s1, s0, 1408
	s_sub_u32 s1, s47, s1
	s_mul_hi_u32 s2, s1, 0x2e8ba2f
	s_mul_i32 s8, s2, 88
	s_sub_u32 s8, s1, s8
	s_mul_i32 s9, s0, 0x5800000
	s_mul_i32 s28, s2, 0x2c0000
	s_add_u32 s9, s9, s28
	s_lshl_b32 s8, s8, 8
	s_add_u32 s9, s9, s8
	s_add_u32 s42, s72, s9
	s_addc_u32 s43, s73, 0
	s_mov_b32 m0, s48
	s_add_u32 s49, s48, 0x400
	global_load_lds_dwordx4 v0, s[42:43] nt
	s_mov_b32 m0, s49
	s_add_u32 s49, s48, 0x800
	global_load_lds_dwordx4 v1, s[42:43] nt
	s_mov_b32 m0, s49
	s_add_u32 s49, s48, 0xc00
	global_load_lds_dwordx4 v2, s[42:43] nt
	s_mov_b32 m0, s49
	s_nop 0
	global_load_lds_dwordx4 v3, s[42:43] nt
	s_branch .Lcv_up_lj

; __device__ __forceinline__ unsigned cvt_pk_bf16(float lo, float hi) { unsigned r; asm volatile("v_cvt_pk_bf16_f32 %0, %1, %2" : "=v"(r) : "v"(lo), "v"(hi)); return r; }
; __device__ __forceinline__ void lds_barrier() { asm volatile("s_waitcnt lgkmcnt(0)" ::: "memory"); __builtin_amdgcn_s_barrier(); asm volatile("" ::: "memory"); }
; __device__ __forceinline__ void convT_job(const float* __restrict__ src, bf16_t* __restrict__ dst, int K, int N, int mode, float* t) {
;     ...
;         lds_barrier();
;         const int n = tid >> 3, k16 = (tid & 7) * 16;
;         float v[16];
; #pragma unroll
;         for (int j = 0; j < 16; ++j) v[j] = t[(k16 + j) * 65 + n];
;         const int nn = n0 + n;
;         const int row = mode == 0 ? nn : (256 * (nn >> 7) + (nn & 127) + (mode == 2 ? 128 : 0));
;         u32x4 w0, w1; w0.x = cvt_pk_bf16(v[0], v[1]); w0.y = cvt_pk_bf16(v[2], v[3]); w0.z = cvt_pk_bf16(v[4], v[5]); w0.w = cvt_pk_bf16(v[6], v[7]);
;         w1.x = cvt_pk_bf16(v[8], v[9]); w1.y = cvt_pk_bf16(v[10], v[11]); w1.z = cvt_pk_bf16(v[12], v[13]); w1.w = cvt_pk_bf16(v[14], v[15]);
;         bf16_t* d = dst + (size_t)row * K + k0 + k16;
;         *(u32x4*)d = w0; *(u32x4*)(d + 8) = w1;
;         lds_barrier();
; __device__ __forceinline__ void phase_convert(const Params& p, unsigned char* smem) {
;     ...
;             convT_job(p.in[5] + wo, (bf16_t*)(p.ws + OFF_DN + (size_t)(l * 2 + f) * SZ_DN), 5632, 2048, 0, t);
.Lcv_up_lj:
	v_add_u32_e32 v7, s41, v4
	ds_read2st64_b32 v[8:9], v7 offset0:0 offset1:1
	ds_read2st64_b32 v[10:11], v7 offset0:2 offset1:3
	ds_read2st64_b32 v[12:13], v7 offset0:4 offset1:5
	ds_read2st64_b32 v[14:15], v7 offset0:6 offset1:7
	ds_read2st64_b32 v[16:17], v7 offset0:8 offset1:9
	ds_read2st64_b32 v[18:19], v7 offset0:10 offset1:11
	ds_read2st64_b32 v[20:21], v7 offset0:12 offset1:13
	ds_read2st64_b32 v[22:23], v7 offset0:14 offset1:15
	s_mul_hi_u32 s0, s40, 0x2e8ba3
	s_mul_i32 s1, s0, 1408
	s_sub_u32 s1, s40, s1
	s_mul_hi_u32 s2, s1, 0x2e8ba2f
	s_mul_i32 s8, s2, 88
	s_sub_u32 s8, s1, s8
	s_lshr_b32 s9, s8, 1
	s_lshl_b32 s9, s9, 8
	s_and_b32 s28, s8, 1
	s_lshl_b32 s28, s28, 6
	s_add_u32 s9, s9, s28
	s_add_u32 s9, s9, 128
	s_mul_i32 s9, s9, 0x1000
	s_mul_i32 s28, s0, 0x5800000
	s_add_u32 s9, s9, s28
	s_lshl_b32 s2, s2, 8
	s_add_u32 s9, s9, s2
	s_add_u32 s9, s9, 0x8000
	s_add_u32 s44, s54, s9
	s_addc_u32 s45, s55, 0
	s_waitcnt lgkmcnt(6)
	v_cvt_pk_bf16_f32 v8, v8, v9
	v_cvt_pk_bf16_f32 v9, v10, v11
	s_waitcnt lgkmcnt(4)
	v_cvt_pk_bf16_f32 v10, v12, v13
	v_cvt_pk_bf16_f32 v11, v14, v15
	s_waitcnt lgkmcnt(2)
	v_cvt_pk_bf16_f32 v12, v16, v17
	v_cvt_pk_bf16_f32 v13, v18, v19
	s_waitcnt lgkmcnt(0)
	v_cvt_pk_bf16_f32 v14, v20, v21
	v_cvt_pk_bf16_f32 v15, v22, v23
	global_store_dwordx4 v5, v[8:11], s[44:45]
	global_store_dwordx4 v5, v[12:15], s[44:45] offset:16
	s_add_u32 s40, s40, s98
	s_add_u32 s41, s41, 0x8000
	s_and_b32 s41, s41, 0x1ffff
	s_cmp_lt_u32 s40, 2816
	s_cbranch_scc1 .Lcv_up_loop
.Lcv_up_skip:
	s_mov_b32 s40, s60
	s_cmp_lt_u32 s40, 2816
	s_cbranch_scc0 .Lcv_down_skip
	v_mov_b32_e32 v29, 0x2000
	v_mov_b32_e32 v28, 0x2c00
	v_mad_u32_u24 v0, v30, v29, v31
	v_mad_u32_u24 v5, v26, v28, v27
	v_add_u32_e32 v1, 0x8000, v0
	v_add_u32_e32 v2, 0x10000, v0
	v_add_u32_e32 v3, 0x18000, v0
	s_barrier
	s_mov_b32 s41, 0
	s_mov_b32 s47, s40
	s_mov_b32 s48, s46
	s_mul_hi_u32 s0, s47, 0x2e8ba3
	s_mul_i32 s1, s0, 1408
	s_sub_u32 s1, s47, s1
	s_mul_hi_u32 s2, s1, 0x8000001
	s_mul_i32 s8, s2, 32
	s_sub_u32 s8, s1, s8
	s_mul_i32 s9, s0, 0x5800000
	s_mul_i32 s28, s2, 0x100000
	s_add_u32 s9, s9, s28
	s_lshl_b32 s8, s8, 8
	s_add_u32 s9, s9, s8
	s_add_u32 s42, s74, s9
	s_addc_u32 s43, s75, 0
	s_mov_b32 m0, s48
	s_add_u32 s49, s48, 0x400
	global_load_lds_dwordx4 v0, s[42:43] nt
	s_mov_b32 m0, s49
	s_add_u32 s49, s48, 0x800
	global_load_lds_dwordx4 v1, s[42:43] nt
	s_mov_b32 m0, s49
	s_add_u32 s49, s48, 0xc00
	global_load_lds_dwordx4 v2, s[42:43] nt
	s_mov_b32 m0, s49
	s_nop 0
	global_load_lds_dwordx4 v3, s[42:43] nt
	global_load_dword v24, v173, s[74:75]
	global_load_dword v24, v173, s[74:75]
	s_add_u32 s47, s40, s98
	s_add_u32 s48, s46, 0x8000
	s_cmp_lt_u32 s47, 2816
	s_cbranch_scc0 .Lcv_down_pd1
	s_mul_hi_u32 s0, s47, 0x2e8ba3
	s_mul_i32 s1, s0, 1408
	s_sub_u32 s1, s47, s1
	s_mul_hi_u32 s2, s1, 0x8000001
	s_mul_i32 s8, s2, 32
	s_sub_u32 s8, s1, s8
	s_mul_i32 s9, s0, 0x5800000
	s_mul_i32 s28, s2, 0x100000
	s_add_u32 s9, s9, s28
	s_lshl_b32 s8, s8, 8
	s_add_u32 s9, s9, s8
	s_add_u32 s42, s74, s9
	s_addc_u32 s43, s75, 0
	s_mov_b32 m0, s48
	s_add_u32 s49, s48, 0x400
	global_load_lds_dwordx4 v0, s[42:43] nt
	s_mov_b32 m0, s49
	s_add_u32 s49, s48, 0x800
	global_load_lds_dwordx4 v1, s[42:43] nt
	s_mov_b32 m0, s49
	s_add_u32 s49, s48, 0xc00
	global_load_lds_dwordx4 v2, s[42:43] nt
	s_mov_b32 m0, s49
	s_nop 0
	global_load_lds_dwordx4 v3, s[42:43] nt
	s_branch .Lcv_down_pj1

; #define CVT_LOAD(tile_) do { const int k0_ = ((tile_) / ntn) << 7, n0_ = ((tile_) % ntn) << 6; \
;         _Pragma("unroll") for (int pp = 0; pp < 4; ++pp) pv[pp] = *(const float4*)(src + (size_t)(k0_ + lk + 32 * pp) * N + n0_ + ln4); } while (0)
; __device__ __forceinline__ void convT_job(const float* __restrict__ src, bf16_t* __restrict__ dst, int K, int N, int mode, float* t) {
;     ...
;         if (tile + (int)gridDim.x < ntiles) CVT_LOAD(tile + (int)gridDim.x);
.Lcv_down_pj1:
	global_load_dword v24, v173, s[74:75]
	global_load_dword v24, v173, s[74:75]
	s_lshl_b32 s47, s98, 1
	s_add_u32 s47, s47, s40
	s_add_u32 s48, s46, 0x10000
	s_cmp_lt_u32 s47, 2816
	s_cbranch_scc0 .Lcv_down_pd2
	s_mul_hi_u32 s0, s47, 0x2e8ba3
	s_mul_i32 s1, s0, 1408
	s_sub_u32 s1, s47, s1
	s_mul_hi_u32 s2, s1, 0x8000001
	s_mul_i32 s8, s2, 32
	s_sub_u32 s8, s1, s8
	s_mul_i32 s9, s0, 0x5800000
	s_mul_i32 s28, s2, 0x100000
	s_add_u32 s9, s9, s28
	s_lshl_b32 s8, s8, 8
	s_add_u32 s9, s9, s8
	s_add_u32 s42, s74, s9
	s_addc_u32 s43, s75, 0
	s_mov_b32 m0, s48
	s_add_u32 s49, s48, 0x400
	global_load_lds_dwordx4 v0, s[42:43] nt
	s_mov_b32 m0, s49
	s_add_u32 s49, s48, 0x800
	global_load_lds_dwordx4 v1, s[42:43] nt
	s_mov_b32 m0, s49
	s_add_u32 s49, s48, 0xc00
	global_load_lds_dwordx4 v2, s[42:43] nt
	s_mov_b32 m0, s49
	s_nop 0
	global_load_lds_dwordx4 v3, s[42:43] nt
	s_branch .Lcv_down_pj2

; #define CVT_LOAD(tile_) do { const int k0_ = ((tile_) / ntn) << 7, n0_ = ((tile_) % ntn) << 6; \
;         _Pragma("unroll") for (int pp = 0; pp < 4; ++pp) pv[pp] = *(const float4*)(src + (size_t)(k0_ + lk + 32 * pp) * N + n0_ + ln4); } while (0)
; __device__ __forceinline__ void convT_job(const float* __restrict__ src, bf16_t* __restrict__ dst, int K, int N, int mode, float* t) {
;     ...
; #pragma unroll 1
;     for (; tile < ntiles; tile += gridDim.x) {
;         const int k0 = (tile / ntn) << 7, n0 = (tile % ntn) << 6;
; #pragma unroll
;         for (int pp = 0; pp < 4; ++pp) { const int k = lk + 32 * pp; t[k * 65 + ln4] = pv[pp].x; t[k * 65 + ln4 + 1] = pv[pp].y; t[k * 65 + ln4 + 2] = pv[pp].z; t[k * 65 + ln4 + 3] = pv[pp].w; }
;         if (tile + (int)gridDim.x < ntiles) CVT_LOAD(tile + (int)gridDim.x);
.Lcv_down_loop:
	s_waitcnt vmcnt(14)
	s_barrier
	s_mul_i32 s47, s98, 3
	s_add_u32 s47, s47, s40
	s_add_u32 s48, s41, 0x18000
	s_and_b32 s48, s48, 0x1ffff
	s_add_u32 s48, s48, s46
	s_cmp_lt_u32 s47, 2816
	s_cbranch_scc0 .Lcv_down_ld
	s_mul_hi_u32 s0, s47, 0x2e8ba3
	s_mul_i32 s1, s0, 1408
	s_sub_u32 s1, s47, s1
	s_mul_hi_u32 s2, s1, 0x8000001
	s_mul_i32 s8, s2, 32
	s_sub_u32 s8, s1, s8
	s_mul_i32 s9, s0, 0x5800000
	s_mul_i32 s28, s2, 0x100000
	s_add_u32 s9, s9, s28
	s_lshl_b32 s8, s8, 8
	s_add_u32 s9, s9, s8
	s_add_u32 s42, s74, s9
	s_addc_u32 s43, s75, 0
	s_mov_b32 m0, s48
	s_add_u32 s49, s48, 0x400
	global_load_lds_dwordx4 v0, s[42:43] nt
	s_mov_b32 m0, s49
	s_add_u32 s49, s48, 0x800
	global_load_lds_dwordx4 v1, s[42:43] nt
	s_mov_b32 m0, s49
	s_add_u32 s49, s48, 0xc00
	global_load_lds_dwordx4 v2, s[42:43] nt
	s_mov_b32 m0, s49
	s_nop 0
	global_load_lds_dwordx4 v3, s[42:43] nt
	s_branch .Lcv_down_lj

; __device__ __forceinline__ unsigned cvt_pk_bf16(float lo, float hi) { unsigned r; asm volatile("v_cvt_pk_bf16_f32 %0, %1, %2" : "=v"(r) : "v"(lo), "v"(hi)); return r; }
; __device__ __forceinline__ void lds_barrier() { asm volatile("s_waitcnt lgkmcnt(0)" ::: "memory"); __builtin_amdgcn_s_barrier(); asm volatile("" ::: "memory"); }
; __device__ __forceinline__ void convT_job(const float* __restrict__ src, bf16_t* __restrict__ dst, int K, int N, int mode, float* t) {
;     ...
;         lds_barrier();
;         const int n = tid >> 3, k16 = (tid & 7) * 16;
;         float v[16];
; #pragma unroll
;         for (int j = 0; j < 16; ++j) v[j] = t[(k16 + j) * 65 + n];
;         const int nn = n0 + n;
;         const int row = mode == 0 ? nn : (256 * (nn >> 7) + (nn & 127) + (mode == 2 ? 128 : 0));
;         u32x4 w0, w1; w0.x = cvt_pk_bf16(v[0], v[1]); w0.y = cvt_pk_bf16(v[2], v[3]); w0.z = cvt_pk_bf16(v[4], v[5]); w0.w = cvt_pk_bf16(v[6], v[7]);
;         w1.x = cvt_pk_bf16(v[8], v[9]); w1.y = cvt_pk_bf16(v[10], v[11]); w1.z = cvt_pk_bf16(v[12], v[13]); w1.w = cvt_pk_bf16(v[14], v[15]);
;         bf16_t* d = dst + (size_t)row * K + k0 + k16;
;         *(u32x4*)d = w0; *(u32x4*)(d + 8) = w1;
;         lds_barrier();
; __device__ __forceinline__ void phase_convert(const Params& p, unsigned char* smem) {
;     ...
;         convT_job(p.in[6] + (size_t)l * 2048 * 5632, (bf16_t*)(p.ws + OFF_IN + (size_t)l * SZ_IN), 2048, 5632, 0, t);
.Lcv_down_lj:
	v_add_u32_e32 v7, s41, v4
	ds_read2st64_b32 v[8:9], v7 offset0:0 offset1:1
	ds_read2st64_b32 v[10:11], v7 offset0:2 offset1:3
	ds_read2st64_b32 v[12:13], v7 offset0:4 offset1:5
	ds_read2st64_b32 v[14:15], v7 offset0:6 offset1:7
	ds_read2st64_b32 v[16:17], v7 offset0:8 offset1:9
	ds_read2st64_b32 v[18:19], v7 offset0:10 offset1:11
	ds_read2st64_b32 v[20:21], v7 offset0:12 offset1:13
	ds_read2st64_b32 v[22:23], v7 offset0:14 offset1:15
	s_mul_hi_u32 s0, s40, 0x2e8ba3
	s_mul_i32 s1, s0, 1408
	s_sub_u32 s1, s40, s1
	s_mul_hi_u32 s2, s1, 0x8000001
	s_mul_i32 s8, s2, 32
	s_sub_u32 s8, s1, s8
	s_lshl_b32 s9, s8, 6
	s_mul_i32 s9, s9, 0x2c00
	s_mul_i32 s28, s0, 0x2c00000
	s_add_u32 s9, s9, s28
	s_lshl_b32 s2, s2, 8
	s_add_u32 s9, s9, s2
	s_add_u32 s9, s9, 0xb008000
	s_add_u32 s44, s54, s9
	s_addc_u32 s45, s55, 0
	s_waitcnt lgkmcnt(6)
	v_cvt_pk_bf16_f32 v8, v8, v9
	v_cvt_pk_bf16_f32 v9, v10, v11
	s_waitcnt lgkmcnt(4)
	v_cvt_pk_bf16_f32 v10, v12, v13
	v_cvt_pk_bf16_f32 v11, v14, v15
	s_waitcnt lgkmcnt(2)
	v_cvt_pk_bf16_f32 v12, v16, v17
	v_cvt_pk_bf16_f32 v13, v18, v19
	s_waitcnt lgkmcnt(0)
	v_cvt_pk_bf16_f32 v14, v20, v21
	v_cvt_pk_bf16_f32 v15, v22, v23
	global_store_dwordx4 v5, v[8:11], s[44:45]
	global_store_dwordx4 v5, v[12:15], s[44:45] offset:16
	s_add_u32 s40, s40, s98
	s_add_u32 s41, s41, 0x8000
	s_and_b32 s41, s41, 0x1ffff
	s_cmp_lt_u32 s40, 2816
	s_cbranch_scc1 .Lcv_down_loop
.Lcv_down_skip:
	s_mov_b32 s40, s60
	s_cmp_lt_u32 s40, 2816
	s_cbranch_scc0 .Lcv_win_skip
	v_mov_b32_e32 v29, 0x5800
	v_mov_b32_e32 v28, 0x1000
	v_mad_u32_u24 v0, v30, v29, v31
	v_mad_u32_u24 v5, v26, v28, v27
	v_add_u32_e32 v1, 0x16000, v0
	v_add_u32_e32 v2, 0x2c000, v0
	v_add_u32_e32 v3, 0x42000, v0
	s_barrier
	s_mov_b32 s41, 0
	s_mov_b32 s47, s40
	s_mov_b32 s48, s46
	s_mul_hi_u32 s0, s47, 0x2e8ba3
	s_mul_i32 s1, s0, 1408
	s_sub_u32 s1, s47, s1
	s_mul_hi_u32 s2, s1, 0x2e8ba2f
	s_mul_i32 s8, s2, 88
	s_sub_u32 s8, s1, s8
	s_mul_i32 s9, s0, 0x2c00000
	s_mul_i32 s28, s2, 0x2c0000
	s_add_u32 s9, s9, s28
	s_lshl_b32 s8, s8, 8
	s_add_u32 s9, s9, s8
	s_add_u32 s42, s76, s9
	s_addc_u32 s43, s77, 0
	s_mov_b32 m0, s48
	s_add_u32 s49, s48, 0x400
	global_load_lds_dwordx4 v0, s[42:43] nt
	s_mov_b32 m0, s49
	s_add_u32 s49, s48, 0x800
	global_load_lds_dwordx4 v1, s[42:43] nt
	s_mov_b32 m0, s49
	s_add_u32 s49, s48, 0xc00
	global_load_lds_dwordx4 v2, s[42:43] nt
	s_mov_b32 m0, s49
	s_nop 0
	global_load_lds_dwordx4 v3, s[42:43] nt
	global_load_dword v24, v173, s[76:77]
	global_load_dword v24, v173, s[76:77]
	s_add_u32 s47, s40, s98
	s_add_u32 s48, s46, 0x8000
	s_cmp_lt_u32 s47, 2816
	s_cbranch_scc0 .Lcv_win_pd1
	s_mul_hi_u32 s0, s47, 0x2e8ba3
	s_mul_i32 s1, s0, 1408
	s_sub_u32 s1, s47, s1
	s_mul_hi_u32 s2, s1, 0x2e8ba2f
	s_mul_i32 s8, s2, 88
	s_sub_u32 s8, s1, s8
	s_mul_i32 s9, s0, 0x2c00000
	s_mul_i32 s28, s2, 0x2c0000
	s_add_u32 s9, s9, s28
	s_lshl_b32 s8, s8, 8
	s_add_u32 s9, s9, s8
	s_add_u32 s42, s76, s9
	s_addc_u32 s43, s77, 0
	s_mov_b32 m0, s48
	s_add_u32 s49, s48, 0x400
	global_load_lds_dwordx4 v0, s[42:43] nt
	s_mov_b32 m0, s49
	s_add_u32 s49, s48, 0x800
	global_load_lds_dwordx4 v1, s[42:43] nt
	s_mov_b32 m0, s49
	s_add_u32 s49, s48, 0xc00
	global_load_lds_dwordx4 v2, s[42:43] nt
	s_mov_b32 m0, s49
	s_nop 0
	global_load_lds_dwordx4 v3, s[42:43] nt
	s_branch .Lcv_win_pj1

; #define CVT_LOAD(tile_) do { const int k0_ = ((tile_) / ntn) << 7, n0_ = ((tile_) % ntn) << 6; \
;         _Pragma("unroll") for (int pp = 0; pp < 4; ++pp) pv[pp] = *(const float4*)(src + (size_t)(k0_ + lk + 32 * pp) * N + n0_ + ln4); } while (0)
; __device__ __forceinline__ void convT_job(const float* __restrict__ src, bf16_t* __restrict__ dst, int K, int N, int mode, float* t) {
;     ...
;         if (tile + (int)gridDim.x < ntiles) CVT_LOAD(tile + (int)gridDim.x);
.Lcv_win_pj1:
	global_load_dword v24, v173, s[76:77]
	global_load_dword v24, v173, s[76:77]
	s_lshl_b32 s47, s98, 1
	s_add_u32 s47, s47, s40
	s_add_u32 s48, s46, 0x10000
	s_cmp_lt_u32 s47, 2816
	s_cbranch_scc0 .Lcv_win_pd2
	s_mul_hi_u32 s0, s47, 0x2e8ba3
	s_mul_i32 s1, s0, 1408
	s_sub_u32 s1, s47, s1
	s_mul_hi_u32 s2, s1, 0x2e8ba2f
	s_mul_i32 s8, s2, 88
	s_sub_u32 s8, s1, s8
	s_mul_i32 s9, s0, 0x2c00000
	s_mul_i32 s28, s2, 0x2c0000
	s_add_u32 s9, s9, s28
	s_lshl_b32 s8, s8, 8
	s_add_u32 s9, s9, s8
	s_add_u32 s42, s76, s9
	s_addc_u32 s43, s77, 0
	s_mov_b32 m0, s48
	s_add_u32 s49, s48, 0x400
	global_load_lds_dwordx4 v0, s[42:43] nt
	s_mov_b32 m0, s49
	s_add_u32 s49, s48, 0x800
	global_load_lds_dwordx4 v1, s[42:43] nt
	s_mov_b32 m0, s49
	s_add_u32 s49, s48, 0xc00
	global_load_lds_dwordx4 v2, s[42:43] nt
	s_mov_b32 m0, s49
	s_nop 0
	global_load_lds_dwordx4 v3, s[42:43] nt
	s_branch .Lcv_win_pj2

; #define CVT_LOAD(tile_) do { const int k0_ = ((tile_) / ntn) << 7, n0_ = ((tile_) % ntn) << 6; \
;         _Pragma("unroll") for (int pp = 0; pp < 4; ++pp) pv[pp] = *(const float4*)(src + (size_t)(k0_ + lk + 32 * pp) * N + n0_ + ln4); } while (0)
; __device__ __forceinline__ void convT_job(const float* __restrict__ src, bf16_t* __restrict__ dst, int K, int N, int mode, float* t) {
;     ...
; #pragma unroll 1
;     for (; tile < ntiles; tile += gridDim.x) {
;         const int k0 = (tile / ntn) << 7, n0 = (tile % ntn) << 6;
; #pragma unroll
;         for (int pp = 0; pp < 4; ++pp) { const int k = lk + 32 * pp; t[k * 65 + ln4] = pv[pp].x; t[k * 65 + ln4 + 1] = pv[pp].y; t[k * 65 + ln4 + 2] = pv[pp].z; t[k * 65 + ln4 + 3] = pv[pp].w; }
;         if (tile + (int)gridDim.x < ntiles) CVT_LOAD(tile + (int)gridDim.x);
.Lcv_win_loop:
	s_waitcnt vmcnt(14)
	s_barrier
	s_mul_i32 s47, s98, 3
	s_add_u32 s47, s47, s40
	s_add_u32 s48, s41, 0x18000
	s_and_b32 s48, s48, 0x1ffff
	s_add_u32 s48, s48, s46
	s_cmp_lt_u32 s47, 2816
	s_cbranch_scc0 .Lcv_win_ld
	s_mul_hi_u32 s0, s47, 0x2e8ba3
	s_mul_i32 s1, s0, 1408
	s_sub_u32 s1, s47, s1
	s_mul_hi_u32 s2, s1, 0x2e8ba2f
	s_mul_i32 s8, s2, 88
	s_sub_u32 s8, s1, s8
	s_mul_i32 s9, s0, 0x2c00000
	s_mul_i32 s28, s2, 0x2c0000
	s_add_u32 s9, s9, s28
	s_lshl_b32 s8, s8, 8
	s_add_u32 s9, s9, s8
	s_add_u32 s42, s76, s9
	s_addc_u32 s43, s77, 0
	s_mov_b32 m0, s48
	s_add_u32 s49, s48, 0x400
	global_load_lds_dwordx4 v0, s[42:43] nt
	s_mov_b32 m0, s49
	s_add_u32 s49, s48, 0x800
	global_load_lds_dwordx4 v1, s[42:43] nt
	s_mov_b32 m0, s49
	s_add_u32 s49, s48, 0xc00
	global_load_lds_dwordx4 v2, s[42:43] nt
	s_mov_b32 m0, s49
	s_nop 0
	global_load_lds_dwordx4 v3, s[42:43] nt
	s_branch .Lcv_win_lj

; __device__ __forceinline__ unsigned cvt_pk_bf16(float lo, float hi) { unsigned r; asm volatile("v_cvt_pk_bf16_f32 %0, %1, %2" : "=v"(r) : "v"(lo), "v"(hi)); return r; }
; __device__ __forceinline__ void lds_barrier() { asm volatile("s_waitcnt lgkmcnt(0)" ::: "memory"); __builtin_amdgcn_s_barrier(); asm volatile("" ::: "memory"); }
; __device__ __forceinline__ void convT_job(const float* __restrict__ src, bf16_t* __restrict__ dst, int K, int N, int mode, float* t) {
;     ...
;         lds_barrier();
;         const int n = tid >> 3, k16 = (tid & 7) * 16;
;         float v[16];
; #pragma unroll
;         for (int j = 0; j < 16; ++j) v[j] = t[(k16 + j) * 65 + n];
;         const int nn = n0 + n;
;         const int row = mode == 0 ? nn : (256 * (nn >> 7) + (nn & 127) + (mode == 2 ? 128 : 0));
;         u32x4 w0, w1; w0.x = cvt_pk_bf16(v[0], v[1]); w0.y = cvt_pk_bf16(v[2], v[3]); w0.z = cvt_pk_bf16(v[4], v[5]); w0.w = cvt_pk_bf16(v[6], v[7]);
;         w1.x = cvt_pk_bf16(v[8], v[9]); w1.y = cvt_pk_bf16(v[10], v[11]); w1.z = cvt_pk_bf16(v[12], v[13]); w1.w = cvt_pk_bf16(v[14], v[15]);
;         bf16_t* d = dst + (size_t)row * K + k0 + k16;
;         *(u32x4*)d = w0; *(u32x4*)(d + 8) = w1;
;         lds_barrier();
; __device__ __forceinline__ void phase_convert(const Params& p, unsigned char* smem) {
;     ...
;         for (int g = 0; g < 4; ++g) {
;             convT_job(p.in[10] + (size_t)(l * 4 + g) * 16384, (bf16_t*)(p.ws + OFF_RGA + (size_t)l * SZ_RG) + g * 16384, 128, 128, 0, t);
.Lcv_win_lj:
	v_add_u32_e32 v7, s41, v4
	ds_read2st64_b32 v[8:9], v7 offset0:0 offset1:1
	ds_read2st64_b32 v[10:11], v7 offset0:2 offset1:3
	ds_read2st64_b32 v[12:13], v7 offset0:4 offset1:5
	ds_read2st64_b32 v[14:15], v7 offset0:6 offset1:7
	ds_read2st64_b32 v[16:17], v7 offset0:8 offset1:9
	ds_read2st64_b32 v[18:19], v7 offset0:10 offset1:11
	ds_read2st64_b32 v[20:21], v7 offset0:12 offset1:13
	ds_read2st64_b32 v[22:23], v7 offset0:14 offset1:15
	s_mul_hi_u32 s0, s40, 0x2e8ba3
	s_mul_i32 s1, s0, 1408
	s_sub_u32 s1, s40, s1
	s_mul_hi_u32 s2, s1, 0x2e8ba2f
	s_mul_i32 s8, s2, 88
	s_sub_u32 s8, s1, s8
	s_lshl_b32 s9, s8, 6
	s_mul_i32 s9, s9, 0x1000
	s_mul_i32 s28, s0, 0x1600000
	s_add_u32 s9, s9, s28
	s_lshl_b32 s2, s2, 8
	s_add_u32 s9, s9, s2
	s_add_u32 s9, s9, 0x10808000
	s_add_u32 s44, s54, s9
	s_addc_u32 s45, s55, 0
	s_waitcnt lgkmcnt(6)
	v_cvt_pk_bf16_f32 v8, v8, v9
	v_cvt_pk_bf16_f32 v9, v10, v11
	s_waitcnt lgkmcnt(4)
	v_cvt_pk_bf16_f32 v10, v12, v13
	v_cvt_pk_bf16_f32 v11, v14, v15
	s_waitcnt lgkmcnt(2)
	v_cvt_pk_bf16_f32 v12, v16, v17
	v_cvt_pk_bf16_f32 v13, v18, v19
	s_waitcnt lgkmcnt(0)
	v_cvt_pk_bf16_f32 v14, v20, v21
	v_cvt_pk_bf16_f32 v15, v22, v23
	global_store_dwordx4 v5, v[8:11], s[44:45]
	global_store_dwordx4 v5, v[12:15], s[44:45] offset:16
	s_add_u32 s40, s40, s98
	s_add_u32 s41, s41, 0x8000
	s_and_b32 s41, s41, 0x1ffff
	s_cmp_lt_u32 s40, 2816
	s_cbranch_scc1 .Lcv_win_loop
.Lcv_win_skip:
	s_mov_b32 s40, s60
	s_cmp_lt_u32 s40, 16
	s_cbranch_scc0 .Lcv_rga_skip
	v_mov_b32_e32 v29, 0x200
	v_mov_b32_e32 v28, 0x100
	v_mad_u32_u24 v0, v30, v29, v31
	v_mad_u32_u24 v5, v26, v28, v27
	v_add_u32_e32 v1, 0x800, v0
	v_add_u32_e32 v2, 0x1000, v0
	v_add_u32_e32 v3, 0x1800, v0
	s_barrier
	s_mov_b32 s41, 0
	s_mov_b32 s47, s40
	s_mov_b32 s48, s46
	s_mul_hi_u32 s0, s47, 0x80000001
	s_mul_i32 s1, s0, 2
	s_sub_u32 s1, s47, s1
	s_mul_hi_u32 s2, s1, 0x80000001
	s_mul_i32 s8, s2, 2
	s_sub_u32 s8, s1, s8
	s_mul_i32 s9, s0, 0x10000
	s_mul_i32 s28, s2, 0x10000
	s_add_u32 s9, s9, s28
	s_lshl_b32 s8, s8, 8
	s_add_u32 s9, s9, s8
	s_add_u32 s42, s84, s9
	s_addc_u32 s43, s85, 0
	s_mov_b32 m0, s48
	s_add_u32 s49, s48, 0x400
	global_load_lds_dwordx4 v0, s[42:43] nt
	s_mov_b32 m0, s49
	s_add_u32 s49, s48, 0x800
	global_load_lds_dwordx4 v1, s[42:43] nt
	s_mov_b32 m0, s49
	s_add_u32 s49, s48, 0xc00
	global_load_lds_dwordx4 v2, s[42:43] nt
	s_mov_b32 m0, s49
	s_nop 0
	global_load_lds_dwordx4 v3, s[42:43] nt
	global_load_dword v24, v173, s[84:85]
	global_load_dword v24, v173, s[84:85]
	s_add_u32 s47, s40, s98
	s_add_u32 s48, s46, 0x8000
	s_cmp_lt_u32 s47, 16
	s_cbranch_scc0 .Lcv_rga_pd1
	s_mul_hi_u32 s0, s47, 0x80000001
	s_mul_i32 s1, s0, 2
	s_sub_u32 s1, s47, s1
	s_mul_hi_u32 s2, s1, 0x80000001
	s_mul_i32 s8, s2, 2
	s_sub_u32 s8, s1, s8
	s_mul_i32 s9, s0, 0x10000
	s_mul_i32 s28, s2, 0x10000
	s_add_u32 s9, s9, s28
	s_lshl_b32 s8, s8, 8
	s_add_u32 s9, s9, s8
	s_add_u32 s42, s84, s9
	s_addc_u32 s43, s85, 0
	s_mov_b32 m0, s48
	s_add_u32 s49, s48, 0x400
	global_load_lds_dwordx4 v0, s[42:43] nt
	s_mov_b32 m0, s49
	s_add_u32 s49, s48, 0x800
	global_load_lds_dwordx4 v1, s[42:43] nt
	s_mov_b32 m0, s49
	s_add_u32 s49, s48, 0xc00
	global_load_lds_dwordx4 v2, s[42:43] nt
	s_mov_b32 m0, s49
	s_nop 0
	global_load_lds_dwordx4 v3, s[42:43] nt
	s_branch .Lcv_rga_pj1

; #define CVT_LOAD(tile_) do { const int k0_ = ((tile_) / ntn) << 7, n0_ = ((tile_) % ntn) << 6; \
;         _Pragma("unroll") for (int pp = 0; pp < 4; ++pp) pv[pp] = *(const float4*)(src + (size_t)(k0_ + lk + 32 * pp) * N + n0_ + ln4); } while (0)
; __device__ __forceinline__ void convT_job(const float* __restrict__ src, bf16_t* __restrict__ dst, int K, int N, int mode, float* t) {
;     ...
;         if (tile + (int)gridDim.x < ntiles) CVT_LOAD(tile + (int)gridDim.x);
.Lcv_rga_pj1:
	global_load_dword v24, v173, s[84:85]
	global_load_dword v24, v173, s[84:85]
	s_lshl_b32 s47, s98, 1
	s_add_u32 s47, s47, s40
	s_add_u32 s48, s46, 0x10000
	s_cmp_lt_u32 s47, 16
	s_cbranch_scc0 .Lcv_rga_pd2
	s_mul_hi_u32 s0, s47, 0x80000001
	s_mul_i32 s1, s0, 2
	s_sub_u32 s1, s47, s1
	s_mul_hi_u32 s2, s1, 0x80000001
	s_mul_i32 s8, s2, 2
	s_sub_u32 s8, s1, s8
	s_mul_i32 s9, s0, 0x10000
	s_mul_i32 s28, s2, 0x10000
	s_add_u32 s9, s9, s28
	s_lshl_b32 s8, s8, 8
	s_add_u32 s9, s9, s8
	s_add_u32 s42, s84, s9
	s_addc_u32 s43, s85, 0
	s_mov_b32 m0, s48
	s_add_u32 s49, s48, 0x400
	global_load_lds_dwordx4 v0, s[42:43] nt
	s_mov_b32 m0, s49
	s_add_u32 s49, s48, 0x800
	global_load_lds_dwordx4 v1, s[42:43] nt
	s_mov_b32 m0, s49
	s_add_u32 s49, s48, 0xc00
	global_load_lds_dwordx4 v2, s[42:43] nt
	s_mov_b32 m0, s49
	s_nop 0
	global_load_lds_dwordx4 v3, s[42:43] nt
	s_branch .Lcv_rga_pj2

; #define CVT_LOAD(tile_) do { const int k0_ = ((tile_) / ntn) << 7, n0_ = ((tile_) % ntn) << 6; \
;         _Pragma("unroll") for (int pp = 0; pp < 4; ++pp) pv[pp] = *(const float4*)(src + (size_t)(k0_ + lk + 32 * pp) * N + n0_ + ln4); } while (0)
; __device__ __forceinline__ void convT_job(const float* __restrict__ src, bf16_t* __restrict__ dst, int K, int N, int mode, float* t) {
;     ...
; #pragma unroll 1
;     for (; tile < ntiles; tile += gridDim.x) {
;         const int k0 = (tile / ntn) << 7, n0 = (tile % ntn) << 6;
; #pragma unroll
;         for (int pp = 0; pp < 4; ++pp) { const int k = lk + 32 * pp; t[k * 65 + ln4] = pv[pp].x; t[k * 65 + ln4 + 1] = pv[pp].y; t[k * 65 + ln4 + 2] = pv[pp].z; t[k * 65 + ln4 + 3] = pv[pp].w; }
;         if (tile + (int)gridDim.x < ntiles) CVT_LOAD(tile + (int)gridDim.x);
.Lcv_rga_loop:
	s_waitcnt vmcnt(14)
	s_barrier
	s_mul_i32 s47, s98, 3
	s_add_u32 s47, s47, s40
	s_add_u32 s48, s41, 0x18000
	s_and_b32 s48, s48, 0x1ffff
	s_add_u32 s48, s48, s46
	s_cmp_lt_u32 s47, 16
	s_cbranch_scc0 .Lcv_rga_ld
	s_mul_hi_u32 s0, s47, 0x80000001
	s_mul_i32 s1, s0, 2
	s_sub_u32 s1, s47, s1
	s_mul_hi_u32 s2, s1, 0x80000001
	s_mul_i32 s8, s2, 2
	s_sub_u32 s8, s1, s8
	s_mul_i32 s9, s0, 0x10000
	s_mul_i32 s28, s2, 0x10000
	s_add_u32 s9, s9, s28
	s_lshl_b32 s8, s8, 8
	s_add_u32 s9, s9, s8
	s_add_u32 s42, s84, s9
	s_addc_u32 s43, s85, 0
	s_mov_b32 m0, s48
	s_add_u32 s49, s48, 0x400
	global_load_lds_dwordx4 v0, s[42:43] nt
	s_mov_b32 m0, s49
	s_add_u32 s49, s48, 0x800
	global_load_lds_dwordx4 v1, s[42:43] nt
	s_mov_b32 m0, s49
	s_add_u32 s49, s48, 0xc00
	global_load_lds_dwordx4 v2, s[42:43] nt
	s_mov_b32 m0, s49
	s_nop 0
	global_load_lds_dwordx4 v3, s[42:43] nt
	s_branch .Lcv_rga_lj

; __device__ __forceinline__ unsigned cvt_pk_bf16(float lo, float hi) { unsigned r; asm volatile("v_cvt_pk_bf16_f32 %0, %1, %2" : "=v"(r) : "v"(lo), "v"(hi)); return r; }
; __device__ __forceinline__ void lds_barrier() { asm volatile("s_waitcnt lgkmcnt(0)" ::: "memory"); __builtin_amdgcn_s_barrier(); asm volatile("" ::: "memory"); }
; __device__ __forceinline__ void convT_job(const float* __restrict__ src, bf16_t* __restrict__ dst, int K, int N, int mode, float* t) {
;     ...
;         lds_barrier();
;         const int n = tid >> 3, k16 = (tid & 7) * 16;
;         float v[16];
; #pragma unroll
;         for (int j = 0; j < 16; ++j) v[j] = t[(k16 + j) * 65 + n];
;         const int nn = n0 + n;
;         const int row = mode == 0 ? nn : (256 * (nn >> 7) + (nn & 127) + (mode == 2 ? 128 : 0));
;         u32x4 w0, w1; w0.x = cvt_pk_bf16(v[0], v[1]); w0.y = cvt_pk_bf16(v[2], v[3]); w0.z = cvt_pk_bf16(v[4], v[5]); w0.w = cvt_pk_bf16(v[6], v[7]);
;         w1.x = cvt_pk_bf16(v[8], v[9]); w1.y = cvt_pk_bf16(v[10], v[11]); w1.z = cvt_pk_bf16(v[12], v[13]); w1.w = cvt_pk_bf16(v[14], v[15]);
;         bf16_t* d = dst + (size_t)row * K + k0 + k16;
;         *(u32x4*)d = w0; *(u32x4*)(d + 8) = w1;
;         lds_barrier();
; __device__ __forceinline__ void phase_convert(const Params& p, unsigned char* smem) {
;     ...
;             convT_job(p.in[12] + (size_t)(l * 4 + g) * 16384, (bf16_t*)(p.ws + OFF_RGX + (size_t)l * SZ_RG) + g * 16384, 128, 128, 0, t);
.Lcv_rga_lj:
	v_add_u32_e32 v7, s41, v4
	ds_read2st64_b32 v[8:9], v7 offset0:0 offset1:1
	ds_read2st64_b32 v[10:11], v7 offset0:2 offset1:3
	ds_read2st64_b32 v[12:13], v7 offset0:4 offset1:5
	ds_read2st64_b32 v[14:15], v7 offset0:6 offset1:7
	ds_read2st64_b32 v[16:17], v7 offset0:8 offset1:9
	ds_read2st64_b32 v[18:19], v7 offset0:10 offset1:11
	ds_read2st64_b32 v[20:21], v7 offset0:12 offset1:13
	ds_read2st64_b32 v[22:23], v7 offset0:14 offset1:15
	s_mul_hi_u32 s0, s40, 0x80000001
	s_mul_i32 s1, s0, 2
	s_sub_u32 s1, s40, s1
	s_mul_hi_u32 s2, s1, 0x80000001
	s_mul_i32 s8, s2, 2
	s_sub_u32 s8, s1, s8
	s_lshl_b32 s9, s8, 6
	s_mul_i32 s9, s9, 0x100
	s_mul_i32 s28, s0, 0x8000
	s_add_u32 s9, s9, s28
	s_lshl_b32 s2, s2, 8
	s_add_u32 s9, s9, s2
	s_add_u32 s9, s9, 0x14408000
	s_add_u32 s44, s54, s9
	s_addc_u32 s45, s55, 0
	s_waitcnt lgkmcnt(6)
	v_cvt_pk_bf16_f32 v8, v8, v9
	v_cvt_pk_bf16_f32 v9, v10, v11
	s_waitcnt lgkmcnt(4)
	v_cvt_pk_bf16_f32 v10, v12, v13
	v_cvt_pk_bf16_f32 v11, v14, v15
	s_waitcnt lgkmcnt(2)
	v_cvt_pk_bf16_f32 v12, v16, v17
	v_cvt_pk_bf16_f32 v13, v18, v19
	s_waitcnt lgkmcnt(0)
	v_cvt_pk_bf16_f32 v14, v20, v21
	v_cvt_pk_bf16_f32 v15, v22, v23
	global_store_dwordx4 v5, v[8:11], s[44:45]
	global_store_dwordx4 v5, v[12:15], s[44:45] offset:16
	s_add_u32 s40, s40, s98
	s_add_u32 s41, s41, 0x8000
	s_and_b32 s41, s41, 0x1ffff
	s_cmp_lt_u32 s40, 16
	s_cbranch_scc1 .Lcv_rga_loop
.Lcv_rga_skip:
	s_mov_b32 s40, s60
	s_cmp_lt_u32 s40, 16
	s_cbranch_scc0 .Lcv_rgx_skip
	v_mov_b32_e32 v29, 0x200
	v_mov_b32_e32 v28, 0x100
	v_mad_u32_u24 v0, v30, v29, v31
	v_mad_u32_u24 v5, v26, v28, v27
	v_add_u32_e32 v1, 0x800, v0
	v_add_u32_e32 v2, 0x1000, v0
	v_add_u32_e32 v3, 0x1800, v0
	s_barrier
	s_mov_b32 s41, 0
	s_mov_b32 s47, s40
	s_mov_b32 s48, s46
	s_mul_hi_u32 s0, s47, 0x80000001
	s_mul_i32 s1, s0, 2
	s_sub_u32 s1, s47, s1
	s_mul_hi_u32 s2, s1, 0x80000001
	s_mul_i32 s8, s2, 2
	s_sub_u32 s8, s1, s8
	s_mul_i32 s9, s0, 0x10000
	s_mul_i32 s28, s2, 0x10000
	s_add_u32 s9, s9, s28
	s_lshl_b32 s8, s8, 8
	s_add_u32 s9, s9, s8
	s_add_u32 s42, s88, s9
	s_addc_u32 s43, s89, 0
	s_mov_b32 m0, s48
	s_add_u32 s49, s48, 0x400
	global_load_lds_dwordx4 v0, s[42:43] nt
	s_mov_b32 m0, s49
	s_add_u32 s49, s48, 0x800
	global_load_lds_dwordx4 v1, s[42:43] nt
	s_mov_b32 m0, s49
	s_add_u32 s49, s48, 0xc00
	global_load_lds_dwordx4 v2, s[42:43] nt
	s_mov_b32 m0, s49
	s_nop 0
	global_load_lds_dwordx4 v3, s[42:43] nt
	global_load_dword v24, v173, s[88:89]
	global_load_dword v24, v173, s[88:89]
	s_add_u32 s47, s40, s98
	s_add_u32 s48, s46, 0x8000
	s_cmp_lt_u32 s47, 16
	s_cbranch_scc0 .Lcv_rgx_pd1
	s_mul_hi_u32 s0, s47, 0x80000001
	s_mul_i32 s1, s0, 2
	s_sub_u32 s1, s47, s1
	s_mul_hi_u32 s2, s1, 0x80000001
	s_mul_i32 s8, s2, 2
	s_sub_u32 s8, s1, s8
	s_mul_i32 s9, s0, 0x10000
	s_mul_i32 s28, s2, 0x10000
	s_add_u32 s9, s9, s28
	s_lshl_b32 s8, s8, 8
	s_add_u32 s9, s9, s8
	s_add_u32 s42, s88, s9
	s_addc_u32 s43, s89, 0
	s_mov_b32 m0, s48
	s_add_u32 s49, s48, 0x400
	global_load_lds_dwordx4 v0, s[42:43] nt
	s_mov_b32 m0, s49
	s_add_u32 s49, s48, 0x800
	global_load_lds_dwordx4 v1, s[42:43] nt
	s_mov_b32 m0, s49
	s_add_u32 s49, s48, 0xc00
	global_load_lds_dwordx4 v2, s[42:43] nt
	s_mov_b32 m0, s49
	s_nop 0
	global_load_lds_dwordx4 v3, s[42:43] nt
	s_branch .Lcv_rgx_pj1

; #define CVT_LOAD(tile_) do { const int k0_ = ((tile_) / ntn) << 7, n0_ = ((tile_) % ntn) << 6; \
;         _Pragma("unroll") for (int pp = 0; pp < 4; ++pp) pv[pp] = *(const float4*)(src + (size_t)(k0_ + lk + 32 * pp) * N + n0_ + ln4); } while (0)
; __device__ __forceinline__ void convT_job(const float* __restrict__ src, bf16_t* __restrict__ dst, int K, int N, int mode, float* t) {
;     ...
;         if (tile + (int)gridDim.x < ntiles) CVT_LOAD(tile + (int)gridDim.x);
.Lcv_rgx_pj1:
	global_load_dword v24, v173, s[88:89]
	global_load_dword v24, v173, s[88:89]
	s_lshl_b32 s47, s98, 1
	s_add_u32 s47, s47, s40
	s_add_u32 s48, s46, 0x10000
	s_cmp_lt_u32 s47, 16
	s_cbranch_scc0 .Lcv_rgx_pd2
	s_mul_hi_u32 s0, s47, 0x80000001
	s_mul_i32 s1, s0, 2
	s_sub_u32 s1, s47, s1
	s_mul_hi_u32 s2, s1, 0x80000001
	s_mul_i32 s8, s2, 2
	s_sub_u32 s8, s1, s8
	s_mul_i32 s9, s0, 0x10000
	s_mul_i32 s28, s2, 0x10000
	s_add_u32 s9, s9, s28
	s_lshl_b32 s8, s8, 8
	s_add_u32 s9, s9, s8
	s_add_u32 s42, s88, s9
	s_addc_u32 s43, s89, 0
	s_mov_b32 m0, s48
	s_add_u32 s49, s48, 0x400
	global_load_lds_dwordx4 v0, s[42:43] nt
	s_mov_b32 m0, s49
	s_add_u32 s49, s48, 0x800
	global_load_lds_dwordx4 v1, s[42:43] nt
	s_mov_b32 m0, s49
	s_add_u32 s49, s48, 0xc00
	global_load_lds_dwordx4 v2, s[42:43] nt
	s_mov_b32 m0, s49
	s_nop 0
	global_load_lds_dwordx4 v3, s[42:43] nt
	s_branch .Lcv_rgx_pj2

; #define CVT_LOAD(tile_) do { const int k0_ = ((tile_) / ntn) << 7, n0_ = ((tile_) % ntn) << 6; \
;         _Pragma("unroll") for (int pp = 0; pp < 4; ++pp) pv[pp] = *(const float4*)(src + (size_t)(k0_ + lk + 32 * pp) * N + n0_ + ln4); } while (0)
; __device__ __forceinline__ void convT_job(const float* __restrict__ src, bf16_t* __restrict__ dst, int K, int N, int mode, float* t) {
;     ...
; #pragma unroll 1
;     for (; tile < ntiles; tile += gridDim.x) {
;         const int k0 = (tile / ntn) << 7, n0 = (tile % ntn) << 6;
; #pragma unroll
;         for (int pp = 0; pp < 4; ++pp) { const int k = lk + 32 * pp; t[k * 65 + ln4] = pv[pp].x; t[k * 65 + ln4 + 1] = pv[pp].y; t[k * 65 + ln4 + 2] = pv[pp].z; t[k * 65 + ln4 + 3] = pv[pp].w; }
;         if (tile + (int)gridDim.x < ntiles) CVT_LOAD(tile + (int)gridDim.x);
.Lcv_rgx_loop:
	s_waitcnt vmcnt(14)
	s_barrier
	s_mul_i32 s47, s98, 3
	s_add_u32 s47, s47, s40
	s_add_u32 s48, s41, 0x18000
	s_and_b32 s48, s48, 0x1ffff
	s_add_u32 s48, s48, s46
	s_cmp_lt_u32 s47, 16
	s_cbranch_scc0 .Lcv_rgx_ld
	s_mul_hi_u32 s0, s47, 0x80000001
	s_mul_i32 s1, s0, 2
	s_sub_u32 s1, s47, s1
	s_mul_hi_u32 s2, s1, 0x80000001
	s_mul_i32 s8, s2, 2
	s_sub_u32 s8, s1, s8
	s_mul_i32 s9, s0, 0x10000
	s_mul_i32 s28, s2, 0x10000
	s_add_u32 s9, s9, s28
	s_lshl_b32 s8, s8, 8
	s_add_u32 s9, s9, s8
	s_add_u32 s42, s88, s9
	s_addc_u32 s43, s89, 0
	s_mov_b32 m0, s48
	s_add_u32 s49, s48, 0x400
	global_load_lds_dwordx4 v0, s[42:43] nt
	s_mov_b32 m0, s49
	s_add_u32 s49, s48, 0x800
	global_load_lds_dwordx4 v1, s[42:43] nt
	s_mov_b32 m0, s49
	s_add_u32 s49, s48, 0xc00
	global_load_lds_dwordx4 v2, s[42:43] nt
	s_mov_b32 m0, s49
	s_nop 0
	global_load_lds_dwordx4 v3, s[42:43] nt
	s_branch .Lcv_rgx_lj

; __device__ __forceinline__ unsigned cvt_pk_bf16(float lo, float hi) { unsigned r; asm volatile("v_cvt_pk_bf16_f32 %0, %1, %2" : "=v"(r) : "v"(lo), "v"(hi)); return r; }
; __device__ __forceinline__ void lds_barrier() { asm volatile("s_waitcnt lgkmcnt(0)" ::: "memory"); __builtin_amdgcn_s_barrier(); asm volatile("" ::: "memory"); }
; __device__ __forceinline__ void convT_job(const float* __restrict__ src, bf16_t* __restrict__ dst, int K, int N, int mode, float* t) {
;     ...
;         lds_barrier();
;         const int n = tid >> 3, k16 = (tid & 7) * 16;
;         float v[16];
; #pragma unroll
;         for (int j = 0; j < 16; ++j) v[j] = t[(k16 + j) * 65 + n];
;         const int nn = n0 + n;
;         const int row = mode == 0 ? nn : (256 * (nn >> 7) + (nn & 127) + (mode == 2 ? 128 : 0));
;         u32x4 w0, w1; w0.x = cvt_pk_bf16(v[0], v[1]); w0.y = cvt_pk_bf16(v[2], v[3]); w0.z = cvt_pk_bf16(v[4], v[5]); w0.w = cvt_pk_bf16(v[6], v[7]);
;         w1.x = cvt_pk_bf16(v[8], v[9]); w1.y = cvt_pk_bf16(v[10], v[11]); w1.z = cvt_pk_bf16(v[12], v[13]); w1.w = cvt_pk_bf16(v[14], v[15]);
;         bf16_t* d = dst + (size_t)row * K + k0 + k16;
;         *(u32x4*)d = w0; *(u32x4*)(d + 8) = w1;
;         lds_barrier();
.Lcv_rgx_lj:
	v_add_u32_e32 v7, s41, v4
	ds_read2st64_b32 v[8:9], v7 offset0:0 offset1:1
	ds_read2st64_b32 v[10:11], v7 offset0:2 offset1:3
	ds_read2st64_b32 v[12:13], v7 offset0:4 offset1:5
	ds_read2st64_b32 v[14:15], v7 offset0:6 offset1:7
	ds_read2st64_b32 v[16:17], v7 offset0:8 offset1:9
	ds_read2st64_b32 v[18:19], v7 offset0:10 offset1:11
	ds_read2st64_b32 v[20:21], v7 offset0:12 offset1:13
	ds_read2st64_b32 v[22:23], v7 offset0:14 offset1:15
	s_mul_hi_u32 s0, s40, 0x80000001
	s_mul_i32 s1, s0, 2
	s_sub_u32 s1, s40, s1
	s_mul_hi_u32 s2, s1, 0x80000001
	s_mul_i32 s8, s2, 2
	s_sub_u32 s8, s1, s8
	s_lshl_b32 s9, s8, 6
	s_mul_i32 s9, s9, 0x100
	s_mul_i32 s28, s0, 0x8000
	s_add_u32 s9, s9, s28
	s_lshl_b32 s2, s2, 8
	s_add_u32 s9, s9, s2
	s_add_u32 s9, s9, 0x14448000
	s_add_u32 s44, s54, s9
	s_addc_u32 s45, s55, 0
	s_waitcnt lgkmcnt(6)
	v_cvt_pk_bf16_f32 v8, v8, v9
	v_cvt_pk_bf16_f32 v9, v10, v11
	s_waitcnt lgkmcnt(4)
	v_cvt_pk_bf16_f32 v10, v12, v13
	v_cvt_pk_bf16_f32 v11, v14, v15
	s_waitcnt lgkmcnt(2)
	v_cvt_pk_bf16_f32 v12, v16, v17
	v_cvt_pk_bf16_f32 v13, v18, v19
	s_waitcnt lgkmcnt(0)
	v_cvt_pk_bf16_f32 v14, v20, v21
	v_cvt_pk_bf16_f32 v15, v22, v23
	global_store_dwordx4 v5, v[8:11], s[44:45]
	global_store_dwordx4 v5, v[12:15], s[44:45] offset:16
	s_add_u32 s40, s40, s98
	s_add_u32 s41, s41, 0x8000
	s_and_b32 s41, s41, 0x1ffff
	s_cmp_lt_u32 s40, 16
	s_cbranch_scc1 .Lcv_rgx_loop

; __global__ void __launch_bounds__(512, 2) mega_fwd(Params p) {
	.amdhsa_kernel _Z8mega_fwd6Params
		.amdhsa_group_segment_fixed_size 0
		.amdhsa_private_segment_fixed_size 0
		.amdhsa_kernarg_size 448
		.amdhsa_user_sgpr_count 2
		.amdhsa_user_sgpr_dispatch_ptr 0
		.amdhsa_user_sgpr_queue_ptr 0
		.amdhsa_user_sgpr_kernarg_segment_ptr 1
		.amdhsa_user_sgpr_dispatch_id 0
		.amdhsa_user_sgpr_kernarg_preload_length 0
		.amdhsa_user_sgpr_kernarg_preload_offset 0
		.amdhsa_user_sgpr_private_segment_size 0
		.amdhsa_uses_dynamic_stack 0
		.amdhsa_enable_private_segment 0
		.amdhsa_system_sgpr_workgroup_id_x 1
		.amdhsa_system_sgpr_workgroup_id_y 0
		.amdhsa_system_sgpr_workgroup_id_z 0
		.amdhsa_system_sgpr_workgroup_info 0
		.amdhsa_system_vgpr_workitem_id 2
		.amdhsa_next_free_vgpr 256
		.amdhsa_next_free_sgpr 102
		.amdhsa_accum_offset 256
		.amdhsa_reserve_vcc 1
		.amdhsa_float_round_mode_32 0
		.amdhsa_float_round_mode_16_64 0
		.amdhsa_float_denorm_mode_32 3
		.amdhsa_float_denorm_mode_16_64 3
		.amdhsa_dx10_clamp 1
		.amdhsa_ieee_mode 1
		.amdhsa_fp16_overflow 0
		.amdhsa_tg_split 0
		.amdhsa_exception_fp_ieee_invalid_op 0
		.amdhsa_exception_fp_denorm_src 0
		.amdhsa_exception_fp_ieee_div_zero 0
		.amdhsa_exception_fp_ieee_overflow 0
		.amdhsa_exception_fp_ieee_underflow 0
		.amdhsa_exception_fp_ieee_inexact 0
		.amdhsa_exception_int_div_zero 0
	.end_amdhsa_kernel

; __global__ void __launch_bounds__(512, 2) mega_fwd(Params p) {
amdhsa.kernels:
  - .agpr_count:     0
    .args:
      - .offset:         0
        .size:           192
        .value_kind:     by_value
      - .offset:         192
        .size:           4
        .value_kind:     hidden_block_count_x
      - .offset:         196
        .size:           4
        .value_kind:     hidden_block_count_y
      - .offset:         200
        .size:           4
        .value_kind:     hidden_block_count_z
      - .offset:         204
        .size:           2
        .value_kind:     hidden_group_size_x
      - .offset:         206
        .size:           2
        .value_kind:     hidden_group_size_y
      - .offset:         208
        .size:           2
        .value_kind:     hidden_group_size_z
      - .offset:         210
        .size:           2
        .value_kind:     hidden_remainder_x
      - .offset:         212
        .size:           2
        .value_kind:     hidden_remainder_y
      - .offset:         214
        .size:           2
        .value_kind:     hidden_remainder_z
      - .offset:         232
        .size:           8
        .value_kind:     hidden_global_offset_x
      - .offset:         240
        .size:           8
        .value_kind:     hidden_global_offset_y
      - .offset:         248
        .size:           8
        .value_kind:     hidden_global_offset_z
      - .offset:         256
        .size:           2
        .value_kind:     hidden_grid_dims
      - .offset:         280
        .size:           8
        .value_kind:     hidden_multigrid_sync_arg
      - .offset:         312
        .size:           4
        .value_kind:     hidden_dynamic_lds_size
    .group_segment_fixed_size: 0
    .kernarg_segment_align: 8
    .kernarg_segment_size: 448
    .language:       OpenCL C
    .language_version:
      - 2
      - 0
    .max_flat_workgroup_size: 512
    .name:           _Z8mega_fwd6Params
    .private_segment_fixed_size: 0
    .sgpr_count:     108
    .sgpr_spill_count: 321
    .symbol:         _Z8mega_fwd6Params.kd
    .uniform_work_group_size: 1
    .uses_dynamic_stack: false
    .vgpr_count:     256
    .vgpr_spill_count: 0
    .wavefront_size: 64
